# GEMM k-step prefetch loads issued after the first MFMA group instead of before the MFMA section
# speedup vs baseline: 1.0163x; 1.0163x over previous
; __device__ void gemm_phase(const u16* __restrict__ Wb, int ldw, const u16* __restrict__ Xb, int ldx, int K,
;                            u16* __restrict__ outb, int ldo, int ntn, int ntiles, u16* lds) {
;     ...
;   for (; q < L; q += nbl) {
;     const int qn = q + nbl;
;     const bool has_next = qn < L;
;     const int qq = has_next ? qn : q;
;     const u16* gwn = Wb + (size_t)(GP_NT(qq) * 128 + lrow) * ldw + lc * 8;
;     const u16* gxn = Xb + (size_t)(GP_MT(qq) * 128 + lrow) * ldx + lc * 8;
;     f32x16 acc[2][2];
; #pragma unroll
;     for (int a = 0; a < 2; ++a)
; #pragma unroll
;       for (int b = 0; b < 2; ++b)
; #pragma unroll
;         for (int i = 0; i < 16; ++i) acc[a][b][i] = 0.f;
;     gs_store(B, lds, lo);
;     __syncthreads();
;     for (int kt = 0; kt < nk; kt += 2) {
;       if (kt + 2 < nk) gs_load(B, gw, ldw, gx, ldx, (kt + 2) * 64);
;       else if (has_next) gs_load(B, gwn, ldw, gxn, ldx, 0);
;       gemm_kstep(lds, wn, wt, r, h, acc);
;       gs_store(A, lds + 2 * TILE_U16, lo);
;       __syncthreads();
.LBB0_598:
	v_mov_b64_e32 v[160:161], v[132:133]
	v_add_co_u32_e32 v162, vcc, s81, v160
	v_mov_b64_e32 v[158:159], v[134:135]
	s_nop 0
	v_addc_co_u32_e32 v163, vcc, 0, v161, vcc
	v_add_co_u32_e32 v164, vcc, s80, v160
	s_waitcnt vmcnt(1)
	ds_write_b128 v188, v[98:101]
	ds_write_b128 v188, v[102:105] offset:4608
	ds_write_b128 v188, v[106:109] offset:9216
	ds_write_b128 v188, v[110:113] offset:13824
	ds_write_b128 v188, v[114:117] offset:18432
	ds_write_b128 v188, v[118:121] offset:23040
	ds_write_b128 v188, v[122:125] offset:27648
	ds_write_b128 v188, v[126:129] offset:32256
	v_addc_co_u32_e32 v165, vcc, 0, v161, vcc
	v_add_co_u32_e32 v166, vcc, s84, v160
	s_waitcnt lgkmcnt(0)
	s_nop 0
	v_addc_co_u32_e32 v167, vcc, 0, v161, vcc
	v_add_co_u32_e32 v168, vcc, s81, v158
	s_barrier
	s_nop 0
	v_addc_co_u32_e32 v169, vcc, 0, v159, vcc
	v_add_co_u32_e32 v170, vcc, s80, v158
	s_nop 1
	v_addc_co_u32_e32 v171, vcc, 0, v159, vcc
	v_add_co_u32_e32 v172, vcc, s84, v158
	global_load_dwordx4 v[98:101], v[160:161], off offset:256
	global_load_dwordx4 v[102:105], v[162:163], off offset:256
	v_addc_co_u32_e32 v173, vcc, 0, v159, vcc
	global_load_dwordx4 v[106:109], v[164:165], off offset:256
	global_load_dwordx4 v[110:113], v[166:167], off offset:256
	global_load_dwordx4 v[114:117], v[158:159], off offset:256
	global_load_dwordx4 v[118:121], v[168:169], off offset:256
	global_load_dwordx4 v[122:125], v[170:171], off offset:256
	global_load_dwordx4 v[126:129], v[172:173], off offset:256
	s_add_i32 s38, s39, s87
	s_cmpk_gt_u32 s38, 0x23f
	s_cselect_b64 s[16:17], -1, 0
	s_cmpk_lt_u32 s38, 0x240
	s_cselect_b64 s[0:1], -1, 0
	s_and_b64 s[40:41], s[0:1], exec
	s_cselect_b32 s40, s38, s39
	s_mul_hi_u32 s41, s40, 0x38e38e39
	s_lshr_b32 s41, s41, 5
	s_mul_i32 s44, s41, 0x90
	s_sub_i32 s40, s40, s44
	s_lshl_b32 s44, s40, 4
	s_and_b32 s40, s40, 7
	s_or_b32 s40, s40, s18
	s_lshl_b32 s41, s41, 10
	s_lshl_b32 s40, s40, 7
	s_and_b32 s44, s44, 0xf80
	s_add_i32 s40, s40, s41
	v_add_u32_e32 v2, s44, v131
	v_add_u32_e32 v4, s40, v131
	v_ashrrev_i32_e32 v3, 31, v2
	v_ashrrev_i32_e32 v5, 31, v4
	v_lshlrev_b64 v[2:3], 11, v[2:3]
	v_lshlrev_b64 v[4:5], 11, v[4:5]
	v_lshl_add_u64 v[132:133], v[136:137], 0, v[2:3]
	v_lshl_add_u64 v[134:135], v[138:139], 0, v[4:5]
	s_setprio 1
	ds_read_b128 v[2:5], v140
	ds_read_b128 v[6:9], v141 offset:18432
	ds_read_b128 v[10:13], v141 offset:23040
	s_waitcnt lgkmcnt(1)
	v_mfma_f32_32x32x16_bf16 v[50:65], v[2:5], v[6:9], 0
	s_waitcnt lgkmcnt(0)
	v_mfma_f32_32x32x16_bf16 v[34:49], v[2:5], v[10:13], 0
	ds_read_b128 v[2:5], v140 offset:4608
	ds_read_b128 v[198:201], v140 offset:32
	ds_read_b128 v[202:205], v141 offset:18464
	ds_read_b128 v[206:209], v141 offset:23072
	s_waitcnt lgkmcnt(1)
	v_mfma_f32_32x32x16_bf16 v[50:65], v[198:201], v[202:205], v[50:65]
	s_waitcnt lgkmcnt(0)
	v_mfma_f32_32x32x16_bf16 v[34:49], v[198:201], v[206:209], v[34:49]
	ds_read_b128 v[198:201], v140 offset:4640
	v_mfma_f32_32x32x16_bf16 v[18:33], v[2:5], v[6:9], 0
	v_mfma_f32_32x32x16_bf16 v[2:17], v[2:5], v[10:13], 0
	s_waitcnt lgkmcnt(0)
	v_mfma_f32_32x32x16_bf16 v[18:33], v[198:201], v[202:205], v[18:33]
	v_mfma_f32_32x32x16_bf16 v[2:17], v[198:201], v[206:209], v[2:17]
	ds_read_b128 v[198:201], v140 offset:64
	ds_read_b128 v[202:205], v141 offset:18496
	ds_read_b128 v[206:209], v141 offset:23104
	s_waitcnt lgkmcnt(1)
	v_mfma_f32_32x32x16_bf16 v[50:65], v[198:201], v[202:205], v[50:65]
	s_waitcnt lgkmcnt(0)
	v_mfma_f32_32x32x16_bf16 v[34:49], v[198:201], v[206:209], v[34:49]
	ds_read_b128 v[198:201], v140 offset:4672
	s_waitcnt lgkmcnt(0)
	v_mfma_f32_32x32x16_bf16 v[18:33], v[198:201], v[202:205], v[18:33]
	v_mfma_f32_32x32x16_bf16 v[2:17], v[198:201], v[206:209], v[2:17]
	ds_read_b128 v[198:201], v140 offset:96
	ds_read_b128 v[202:205], v141 offset:18528
	ds_read_b128 v[206:209], v141 offset:23136
	s_waitcnt lgkmcnt(1)
	v_mfma_f32_32x32x16_bf16 v[50:65], v[198:201], v[202:205], v[50:65]
	s_waitcnt lgkmcnt(0)
	v_mfma_f32_32x32x16_bf16 v[34:49], v[198:201], v[206:209], v[34:49]
	ds_read_b128 v[198:201], v140 offset:4704
	s_waitcnt lgkmcnt(0)
	v_mfma_f32_32x32x16_bf16 v[18:33], v[198:201], v[202:205], v[18:33]
	v_mfma_f32_32x32x16_bf16 v[2:17], v[198:201], v[206:209], v[2:17]
	s_setprio 0
	ds_write_b128 v188, v[66:69] offset:36864
	ds_write_b128 v188, v[70:73] offset:41472
	ds_write_b128 v188, v[74:77] offset:46080
	ds_write_b128 v188, v[78:81] offset:50688
	ds_write_b128 v188, v[82:85] offset:55296
	ds_write_b128 v188, v[86:89] offset:59904
	ds_write_b128 v188, v[90:93] offset:64512
	s_waitcnt vmcnt(8)
	ds_write_b128 v189, v[94:97] offset:13824
	s_waitcnt lgkmcnt(0)
	s_barrier
; __device__ __forceinline__ void gemm_kstep(const u16* sb, int wn, int wt, int r, int h, f32x16 (&acc)[2][2]) {
;   const u16* bw = sb + (wn * 64 + r) * LDT + h * 8;
;   const u16* bx = sb + TILE_U16 + (wt * 64 + r) * LDT + h * 8;
;   __builtin_amdgcn_s_setprio(1);
; #pragma unroll
;   for (int ks = 0; ks < 4; ++ks) {
;     bf16x8 a0 = *(const bf16x8*)(bw + ks * 16);
;     bf16x8 a1 = *(const bf16x8*)(bw + 32 * LDT + ks * 16);
;     bf16x8 b0 = *(const bf16x8*)(bx + ks * 16);
;     bf16x8 b1 = *(const bf16x8*)(bx + 32 * LDT + ks * 16);
;     acc[0][0] = mfma32(a0, b0, acc[0][0]);
;     acc[0][1] = mfma32(a0, b1, acc[0][1]);
;     acc[1][0] = mfma32(a1, b0, acc[1][0]);
;     acc[1][1] = mfma32(a1, b1, acc[1][1]);
;   }
;   __builtin_amdgcn_s_setprio(0);
; }
; __device__ void gemm_phase(const u16* __restrict__ Wb, int ldw, const u16* __restrict__ Xb, int ldx, int K,
;                            u16* __restrict__ outb, int ldo, int ntn, int ntiles, u16* lds) {
;     ...
;     for (int kt = 0; kt < nk; kt += 2) {
;       if (kt + 2 < nk) gs_load(B, gw, ldw, gx, ldx, (kt + 2) * 64);
;       else if (has_next) gs_load(B, gwn, ldw, gxn, ldx, 0);
;       gemm_kstep(lds, wn, wt, r, h, acc);
;       gs_store(A, lds + 2 * TILE_U16, lo);
;       __syncthreads();
;       if (kt + 3 < nk) gs_load(A, gw, ldw, gx, ldx, (kt + 3) * 64);
;       else if (has_next) gs_load(A, gwn, ldw, gxn, ldx, 64);
;       gemm_kstep(lds + 2 * TILE_U16, wn, wt, r, h, acc);
;       if (kt + 2 < nk) gs_store(B, lds, lo);
;       __syncthreads();
;     }
	s_setprio 1
	ds_read_b128 v[198:201], v140 offset:36864
	ds_read_b128 v[202:205], v141 offset:55296
	ds_read_b128 v[206:209], v141 offset:59904
	ds_read_b128 v[214:217], v140 offset:41472
	ds_read_b128 v[218:221], v140 offset:36896
	ds_read_b128 v[222:225], v141 offset:55328
	ds_read_b128 v[226:229], v141 offset:59936
	ds_read_b128 v[230:233], v140 offset:41504
	s_waitcnt lgkmcnt(4)
	v_mfma_f32_32x32x16_bf16 v[50:65], v[198:201], v[202:205], v[50:65]
	v_mfma_f32_32x32x16_bf16 v[34:49], v[198:201], v[206:209], v[34:49]
	v_mfma_f32_32x32x16_bf16 v[18:33], v[214:217], v[202:205], v[18:33]
	v_mfma_f32_32x32x16_bf16 v[2:17], v[214:217], v[206:209], v[2:17]
	global_load_dwordx4 v[66:69], v[160:161], off offset:384
	global_load_dwordx4 v[70:73], v[162:163], off offset:384
	global_load_dwordx4 v[74:77], v[164:165], off offset:384
	global_load_dwordx4 v[78:81], v[166:167], off offset:384
	global_load_dwordx4 v[82:85], v[158:159], off offset:384
	global_load_dwordx4 v[86:89], v[168:169], off offset:384
	global_load_dwordx4 v[90:93], v[170:171], off offset:384
	global_load_dwordx4 v[94:97], v[172:173], off offset:384
	ds_read_b128 v[198:201], v140 offset:36928
	ds_read_b128 v[202:205], v141 offset:55360
	ds_read_b128 v[206:209], v141 offset:59968
	ds_read_b128 v[214:217], v140 offset:41536
	s_waitcnt lgkmcnt(4)
	v_mfma_f32_32x32x16_bf16 v[50:65], v[218:221], v[222:225], v[50:65]
	v_mfma_f32_32x32x16_bf16 v[34:49], v[218:221], v[226:229], v[34:49]
	v_mfma_f32_32x32x16_bf16 v[18:33], v[230:233], v[222:225], v[18:33]
	v_mfma_f32_32x32x16_bf16 v[2:17], v[230:233], v[226:229], v[2:17]
	ds_read_b128 v[218:221], v140 offset:36960
	ds_read_b128 v[222:225], v141 offset:55392
	ds_read_b128 v[226:229], v141 offset:60000
	ds_read_b128 v[230:233], v140 offset:41568
	s_waitcnt lgkmcnt(4)
	v_mfma_f32_32x32x16_bf16 v[50:65], v[198:201], v[202:205], v[50:65]
	v_mfma_f32_32x32x16_bf16 v[34:49], v[198:201], v[206:209], v[34:49]
	v_mfma_f32_32x32x16_bf16 v[18:33], v[214:217], v[202:205], v[18:33]
	v_mfma_f32_32x32x16_bf16 v[2:17], v[214:217], v[206:209], v[2:17]
	s_waitcnt lgkmcnt(0)
	v_mfma_f32_32x32x16_bf16 v[50:65], v[218:221], v[222:225], v[50:65]
	v_mfma_f32_32x32x16_bf16 v[34:49], v[218:221], v[226:229], v[34:49]
	v_mfma_f32_32x32x16_bf16 v[18:33], v[230:233], v[222:225], v[18:33]
	v_mfma_f32_32x32x16_bf16 v[2:17], v[230:233], v[226:229], v[2:17]
	s_setprio 0
	s_waitcnt vmcnt(8)
	ds_write_b128 v188, v[98:101]
	ds_write_b128 v188, v[102:105] offset:4608
	ds_write_b128 v188, v[106:109] offset:9216
	ds_write_b128 v188, v[110:113] offset:13824
	ds_write_b128 v188, v[114:117] offset:18432
	ds_write_b128 v188, v[118:121] offset:23040
	ds_write_b128 v188, v[122:125] offset:27648
	ds_write_b128 v188, v[126:129] offset:32256
	s_waitcnt lgkmcnt(0)
	s_barrier
	s_setprio 1
	ds_read_b128 v[198:201], v140
	ds_read_b128 v[202:205], v141 offset:18432
	ds_read_b128 v[206:209], v141 offset:23040
	ds_read_b128 v[214:217], v140 offset:4608
	ds_read_b128 v[218:221], v140 offset:32
	ds_read_b128 v[222:225], v141 offset:18464
	ds_read_b128 v[226:229], v141 offset:23072
	ds_read_b128 v[230:233], v140 offset:4640
	s_waitcnt lgkmcnt(4)
	v_mfma_f32_32x32x16_bf16 v[50:65], v[198:201], v[202:205], v[50:65]
	v_mfma_f32_32x32x16_bf16 v[34:49], v[198:201], v[206:209], v[34:49]
	v_mfma_f32_32x32x16_bf16 v[18:33], v[214:217], v[202:205], v[18:33]
	v_mfma_f32_32x32x16_bf16 v[2:17], v[214:217], v[206:209], v[2:17]
	global_load_dwordx4 v[98:101], v[160:161], off offset:512
	global_load_dwordx4 v[102:105], v[162:163], off offset:512
	global_load_dwordx4 v[106:109], v[164:165], off offset:512
	global_load_dwordx4 v[110:113], v[166:167], off offset:512
	global_load_dwordx4 v[114:117], v[158:159], off offset:512
	global_load_dwordx4 v[118:121], v[168:169], off offset:512
	global_load_dwordx4 v[122:125], v[170:171], off offset:512
	global_load_dwordx4 v[126:129], v[172:173], off offset:512
	ds_read_b128 v[198:201], v140 offset:64
	ds_read_b128 v[202:205], v141 offset:18496
	ds_read_b128 v[206:209], v141 offset:23104
	ds_read_b128 v[214:217], v140 offset:4672
	s_waitcnt lgkmcnt(4)
	v_mfma_f32_32x32x16_bf16 v[50:65], v[218:221], v[222:225], v[50:65]
	v_mfma_f32_32x32x16_bf16 v[34:49], v[218:221], v[226:229], v[34:49]
	v_mfma_f32_32x32x16_bf16 v[18:33], v[230:233], v[222:225], v[18:33]
	v_mfma_f32_32x32x16_bf16 v[2:17], v[230:233], v[226:229], v[2:17]
	ds_read_b128 v[218:221], v140 offset:96
	ds_read_b128 v[222:225], v141 offset:18528
	ds_read_b128 v[226:229], v141 offset:23136
	ds_read_b128 v[230:233], v140 offset:4704
	s_waitcnt lgkmcnt(4)
	v_mfma_f32_32x32x16_bf16 v[50:65], v[198:201], v[202:205], v[50:65]
	v_mfma_f32_32x32x16_bf16 v[34:49], v[198:201], v[206:209], v[34:49]
	v_mfma_f32_32x32x16_bf16 v[18:33], v[214:217], v[202:205], v[18:33]
	v_mfma_f32_32x32x16_bf16 v[2:17], v[214:217], v[206:209], v[2:17]
	s_waitcnt lgkmcnt(0)
	v_mfma_f32_32x32x16_bf16 v[50:65], v[218:221], v[222:225], v[50:65]
	v_mfma_f32_32x32x16_bf16 v[34:49], v[218:221], v[226:229], v[34:49]
	v_mfma_f32_32x32x16_bf16 v[18:33], v[230:233], v[222:225], v[18:33]
	v_mfma_f32_32x32x16_bf16 v[2:17], v[230:233], v[226:229], v[2:17]
	s_setprio 0
	s_waitcnt vmcnt(8)
	ds_write_b128 v188, v[66:69] offset:36864
	ds_write_b128 v188, v[70:73] offset:41472
	ds_write_b128 v188, v[74:77] offset:46080
	ds_write_b128 v188, v[78:81] offset:50688
	ds_write_b128 v188, v[82:85] offset:55296
	ds_write_b128 v188, v[86:89] offset:59904
	ds_write_b128 v188, v[90:93] offset:64512
	ds_write_b128 v189, v[94:97] offset:13824
	s_waitcnt lgkmcnt(0)
	s_barrier
; __device__ __forceinline__ void gemm_kstep(const u16* sb, int wn, int wt, int r, int h, f32x16 (&acc)[2][2]) {
;   const u16* bw = sb + (wn * 64 + r) * LDT + h * 8;
;   const u16* bx = sb + TILE_U16 + (wt * 64 + r) * LDT + h * 8;
;   __builtin_amdgcn_s_setprio(1);
; #pragma unroll
;   for (int ks = 0; ks < 4; ++ks) {
;     bf16x8 a0 = *(const bf16x8*)(bw + ks * 16);
;     bf16x8 a1 = *(const bf16x8*)(bw + 32 * LDT + ks * 16);
;     bf16x8 b0 = *(const bf16x8*)(bx + ks * 16);
;     bf16x8 b1 = *(const bf16x8*)(bx + 32 * LDT + ks * 16);
;     acc[0][0] = mfma32(a0, b0, acc[0][0]);
;     acc[0][1] = mfma32(a0, b1, acc[0][1]);
;     acc[1][0] = mfma32(a1, b0, acc[1][0]);
;     acc[1][1] = mfma32(a1, b1, acc[1][1]);
;   }
;   __builtin_amdgcn_s_setprio(0);
; }
; __device__ void gemm_phase(const u16* __restrict__ Wb, int ldw, const u16* __restrict__ Xb, int ldx, int K,
;                            u16* __restrict__ outb, int ldo, int ntn, int ntiles, u16* lds) {
;     ...
;     for (int kt = 0; kt < nk; kt += 2) {
;       if (kt + 2 < nk) gs_load(B, gw, ldw, gx, ldx, (kt + 2) * 64);
;       else if (has_next) gs_load(B, gwn, ldw, gxn, ldx, 0);
;       gemm_kstep(lds, wn, wt, r, h, acc);
;       gs_store(A, lds + 2 * TILE_U16, lo);
;       __syncthreads();
;       if (kt + 3 < nk) gs_load(A, gw, ldw, gx, ldx, (kt + 3) * 64);
;       else if (has_next) gs_load(A, gwn, ldw, gxn, ldx, 64);
;       gemm_kstep(lds + 2 * TILE_U16, wn, wt, r, h, acc);
;       if (kt + 2 < nk) gs_store(B, lds, lo);
;       __syncthreads();
;     }
	s_setprio 1
	ds_read_b128 v[198:201], v140 offset:36864
	ds_read_b128 v[202:205], v141 offset:55296
	ds_read_b128 v[206:209], v141 offset:59904
	ds_read_b128 v[214:217], v140 offset:41472
	ds_read_b128 v[218:221], v140 offset:36896
	ds_read_b128 v[222:225], v141 offset:55328
	ds_read_b128 v[226:229], v141 offset:59936
	ds_read_b128 v[230:233], v140 offset:41504
	s_waitcnt lgkmcnt(4)
	v_mfma_f32_32x32x16_bf16 v[50:65], v[198:201], v[202:205], v[50:65]
	v_mfma_f32_32x32x16_bf16 v[34:49], v[198:201], v[206:209], v[34:49]
	v_mfma_f32_32x32x16_bf16 v[18:33], v[214:217], v[202:205], v[18:33]
	v_mfma_f32_32x32x16_bf16 v[2:17], v[214:217], v[206:209], v[2:17]
	global_load_dwordx4 v[66:69], v[160:161], off offset:640
	global_load_dwordx4 v[70:73], v[162:163], off offset:640
	global_load_dwordx4 v[74:77], v[164:165], off offset:640
	global_load_dwordx4 v[78:81], v[166:167], off offset:640
	global_load_dwordx4 v[82:85], v[158:159], off offset:640
	global_load_dwordx4 v[86:89], v[168:169], off offset:640
	global_load_dwordx4 v[90:93], v[170:171], off offset:640
	global_load_dwordx4 v[94:97], v[172:173], off offset:640
	ds_read_b128 v[198:201], v140 offset:36928
	ds_read_b128 v[202:205], v141 offset:55360
	ds_read_b128 v[206:209], v141 offset:59968
	ds_read_b128 v[214:217], v140 offset:41536
	s_waitcnt lgkmcnt(4)
	v_mfma_f32_32x32x16_bf16 v[50:65], v[218:221], v[222:225], v[50:65]
	v_mfma_f32_32x32x16_bf16 v[34:49], v[218:221], v[226:229], v[34:49]
	v_mfma_f32_32x32x16_bf16 v[18:33], v[230:233], v[222:225], v[18:33]
	v_mfma_f32_32x32x16_bf16 v[2:17], v[230:233], v[226:229], v[2:17]
	ds_read_b128 v[218:221], v140 offset:36960
	ds_read_b128 v[222:225], v141 offset:55392
	ds_read_b128 v[226:229], v141 offset:60000
	ds_read_b128 v[230:233], v140 offset:41568
	s_waitcnt lgkmcnt(4)
	v_mfma_f32_32x32x16_bf16 v[50:65], v[198:201], v[202:205], v[50:65]
	v_mfma_f32_32x32x16_bf16 v[34:49], v[198:201], v[206:209], v[34:49]
	v_mfma_f32_32x32x16_bf16 v[18:33], v[214:217], v[202:205], v[18:33]
	v_mfma_f32_32x32x16_bf16 v[2:17], v[214:217], v[206:209], v[2:17]
	s_waitcnt lgkmcnt(0)
	v_mfma_f32_32x32x16_bf16 v[50:65], v[218:221], v[222:225], v[50:65]
	v_mfma_f32_32x32x16_bf16 v[34:49], v[218:221], v[226:229], v[34:49]
	v_mfma_f32_32x32x16_bf16 v[18:33], v[230:233], v[222:225], v[18:33]
	v_mfma_f32_32x32x16_bf16 v[2:17], v[230:233], v[226:229], v[2:17]
	s_setprio 0
	s_waitcnt vmcnt(8)
	ds_write_b128 v188, v[98:101]
	ds_write_b128 v188, v[102:105] offset:4608
	ds_write_b128 v188, v[106:109] offset:9216
	ds_write_b128 v188, v[110:113] offset:13824
	ds_write_b128 v188, v[114:117] offset:18432
	ds_write_b128 v188, v[118:121] offset:23040
	ds_write_b128 v188, v[122:125] offset:27648
	ds_write_b128 v188, v[126:129] offset:32256
	s_waitcnt lgkmcnt(0)
	s_barrier
	s_setprio 1
	ds_read_b128 v[198:201], v140
	ds_read_b128 v[202:205], v141 offset:18432
	ds_read_b128 v[206:209], v141 offset:23040
	ds_read_b128 v[214:217], v140 offset:4608
	ds_read_b128 v[218:221], v140 offset:32
	ds_read_b128 v[222:225], v141 offset:18464
	ds_read_b128 v[226:229], v141 offset:23072
	ds_read_b128 v[230:233], v140 offset:4640
	s_waitcnt lgkmcnt(4)
	v_mfma_f32_32x32x16_bf16 v[50:65], v[198:201], v[202:205], v[50:65]
	v_mfma_f32_32x32x16_bf16 v[34:49], v[198:201], v[206:209], v[34:49]
	v_mfma_f32_32x32x16_bf16 v[18:33], v[214:217], v[202:205], v[18:33]
	v_mfma_f32_32x32x16_bf16 v[2:17], v[214:217], v[206:209], v[2:17]
	global_load_dwordx4 v[98:101], v[160:161], off offset:768
	global_load_dwordx4 v[102:105], v[162:163], off offset:768
	global_load_dwordx4 v[106:109], v[164:165], off offset:768
	global_load_dwordx4 v[110:113], v[166:167], off offset:768
	global_load_dwordx4 v[114:117], v[158:159], off offset:768
	global_load_dwordx4 v[118:121], v[168:169], off offset:768
	global_load_dwordx4 v[122:125], v[170:171], off offset:768
	global_load_dwordx4 v[126:129], v[172:173], off offset:768
	ds_read_b128 v[198:201], v140 offset:64
	ds_read_b128 v[202:205], v141 offset:18496
	ds_read_b128 v[206:209], v141 offset:23104
	ds_read_b128 v[214:217], v140 offset:4672
	s_waitcnt lgkmcnt(4)
	v_mfma_f32_32x32x16_bf16 v[50:65], v[218:221], v[222:225], v[50:65]
	v_mfma_f32_32x32x16_bf16 v[34:49], v[218:221], v[226:229], v[34:49]
	v_mfma_f32_32x32x16_bf16 v[18:33], v[230:233], v[222:225], v[18:33]
	v_mfma_f32_32x32x16_bf16 v[2:17], v[230:233], v[226:229], v[2:17]
	ds_read_b128 v[218:221], v140 offset:96
	ds_read_b128 v[222:225], v141 offset:18528
	ds_read_b128 v[226:229], v141 offset:23136
	ds_read_b128 v[230:233], v140 offset:4704
	s_waitcnt lgkmcnt(4)
	v_mfma_f32_32x32x16_bf16 v[50:65], v[198:201], v[202:205], v[50:65]
	v_mfma_f32_32x32x16_bf16 v[34:49], v[198:201], v[206:209], v[34:49]
	v_mfma_f32_32x32x16_bf16 v[18:33], v[214:217], v[202:205], v[18:33]
	v_mfma_f32_32x32x16_bf16 v[2:17], v[214:217], v[206:209], v[2:17]
	s_waitcnt lgkmcnt(0)
	v_mfma_f32_32x32x16_bf16 v[50:65], v[218:221], v[222:225], v[50:65]
	v_mfma_f32_32x32x16_bf16 v[34:49], v[218:221], v[226:229], v[34:49]
	v_mfma_f32_32x32x16_bf16 v[18:33], v[230:233], v[222:225], v[18:33]
	v_mfma_f32_32x32x16_bf16 v[2:17], v[230:233], v[226:229], v[2:17]
	s_setprio 0
	s_waitcnt vmcnt(8)
	ds_write_b128 v188, v[66:69] offset:36864
	ds_write_b128 v188, v[70:73] offset:41472
	ds_write_b128 v188, v[74:77] offset:46080
	ds_write_b128 v188, v[78:81] offset:50688
	ds_write_b128 v188, v[82:85] offset:55296
	ds_write_b128 v188, v[86:89] offset:59904
	ds_write_b128 v188, v[90:93] offset:64512
	ds_write_b128 v189, v[94:97] offset:13824
	s_waitcnt lgkmcnt(0)
	s_barrier
; __device__ __forceinline__ void gemm_kstep(const u16* sb, int wn, int wt, int r, int h, f32x16 (&acc)[2][2]) {
;   const u16* bw = sb + (wn * 64 + r) * LDT + h * 8;
;   const u16* bx = sb + TILE_U16 + (wt * 64 + r) * LDT + h * 8;
;   __builtin_amdgcn_s_setprio(1);
; #pragma unroll
;   for (int ks = 0; ks < 4; ++ks) {
;     bf16x8 a0 = *(const bf16x8*)(bw + ks * 16);
;     bf16x8 a1 = *(const bf16x8*)(bw + 32 * LDT + ks * 16);
;     bf16x8 b0 = *(const bf16x8*)(bx + ks * 16);
;     bf16x8 b1 = *(const bf16x8*)(bx + 32 * LDT + ks * 16);
;     acc[0][0] = mfma32(a0, b0, acc[0][0]);
;     acc[0][1] = mfma32(a0, b1, acc[0][1]);
;     acc[1][0] = mfma32(a1, b0, acc[1][0]);
;     acc[1][1] = mfma32(a1, b1, acc[1][1]);
;   }
;   __builtin_amdgcn_s_setprio(0);
; }
; __device__ void gemm_phase(const u16* __restrict__ Wb, int ldw, const u16* __restrict__ Xb, int ldx, int K,
;                            u16* __restrict__ outb, int ldo, int ntn, int ntiles, u16* lds) {
;     ...
;     for (int kt = 0; kt < nk; kt += 2) {
;       if (kt + 2 < nk) gs_load(B, gw, ldw, gx, ldx, (kt + 2) * 64);
;       else if (has_next) gs_load(B, gwn, ldw, gxn, ldx, 0);
;       gemm_kstep(lds, wn, wt, r, h, acc);
;       gs_store(A, lds + 2 * TILE_U16, lo);
;       __syncthreads();
;       if (kt + 3 < nk) gs_load(A, gw, ldw, gx, ldx, (kt + 3) * 64);
;       else if (has_next) gs_load(A, gwn, ldw, gxn, ldx, 64);
;       gemm_kstep(lds + 2 * TILE_U16, wn, wt, r, h, acc);
;       if (kt + 2 < nk) gs_store(B, lds, lo);
;       __syncthreads();
;     }
	s_setprio 1
	ds_read_b128 v[198:201], v140 offset:36864
	ds_read_b128 v[202:205], v141 offset:55296
	ds_read_b128 v[206:209], v141 offset:59904
	ds_read_b128 v[214:217], v140 offset:41472
	ds_read_b128 v[218:221], v140 offset:36896
	ds_read_b128 v[222:225], v141 offset:55328
	ds_read_b128 v[226:229], v141 offset:59936
	ds_read_b128 v[230:233], v140 offset:41504
	s_waitcnt lgkmcnt(4)
	v_mfma_f32_32x32x16_bf16 v[50:65], v[198:201], v[202:205], v[50:65]
	v_mfma_f32_32x32x16_bf16 v[34:49], v[198:201], v[206:209], v[34:49]
	v_mfma_f32_32x32x16_bf16 v[18:33], v[214:217], v[202:205], v[18:33]
	v_mfma_f32_32x32x16_bf16 v[2:17], v[214:217], v[206:209], v[2:17]
	global_load_dwordx4 v[66:69], v[160:161], off offset:896
	global_load_dwordx4 v[70:73], v[162:163], off offset:896
	global_load_dwordx4 v[74:77], v[164:165], off offset:896
	global_load_dwordx4 v[78:81], v[166:167], off offset:896
	global_load_dwordx4 v[82:85], v[158:159], off offset:896
	global_load_dwordx4 v[86:89], v[168:169], off offset:896
	global_load_dwordx4 v[90:93], v[170:171], off offset:896
	global_load_dwordx4 v[94:97], v[172:173], off offset:896
	ds_read_b128 v[198:201], v140 offset:36928
	ds_read_b128 v[202:205], v141 offset:55360
	ds_read_b128 v[206:209], v141 offset:59968
	ds_read_b128 v[214:217], v140 offset:41536
	s_waitcnt lgkmcnt(4)
	v_mfma_f32_32x32x16_bf16 v[50:65], v[218:221], v[222:225], v[50:65]
	v_mfma_f32_32x32x16_bf16 v[34:49], v[218:221], v[226:229], v[34:49]
	v_mfma_f32_32x32x16_bf16 v[18:33], v[230:233], v[222:225], v[18:33]
	v_mfma_f32_32x32x16_bf16 v[2:17], v[230:233], v[226:229], v[2:17]
	ds_read_b128 v[218:221], v140 offset:36960
	ds_read_b128 v[222:225], v141 offset:55392
	ds_read_b128 v[226:229], v141 offset:60000
	ds_read_b128 v[230:233], v140 offset:41568
	s_waitcnt lgkmcnt(4)
	v_mfma_f32_32x32x16_bf16 v[50:65], v[198:201], v[202:205], v[50:65]
	v_mfma_f32_32x32x16_bf16 v[34:49], v[198:201], v[206:209], v[34:49]
	v_mfma_f32_32x32x16_bf16 v[18:33], v[214:217], v[202:205], v[18:33]
	v_mfma_f32_32x32x16_bf16 v[2:17], v[214:217], v[206:209], v[2:17]
	s_waitcnt lgkmcnt(0)
	v_mfma_f32_32x32x16_bf16 v[50:65], v[218:221], v[222:225], v[50:65]
	v_mfma_f32_32x32x16_bf16 v[34:49], v[218:221], v[226:229], v[34:49]
	v_mfma_f32_32x32x16_bf16 v[18:33], v[230:233], v[222:225], v[18:33]
	v_mfma_f32_32x32x16_bf16 v[2:17], v[230:233], v[226:229], v[2:17]
	s_setprio 0
	s_waitcnt vmcnt(8)
	ds_write_b128 v188, v[98:101]
	ds_write_b128 v188, v[102:105] offset:4608
	ds_write_b128 v188, v[106:109] offset:9216
	ds_write_b128 v188, v[110:113] offset:13824
	ds_write_b128 v188, v[114:117] offset:18432
	ds_write_b128 v188, v[118:121] offset:23040
	ds_write_b128 v188, v[122:125] offset:27648
	ds_write_b128 v188, v[126:129] offset:32256
	s_waitcnt lgkmcnt(0)
	s_barrier
	s_setprio 1
	ds_read_b128 v[198:201], v140
	ds_read_b128 v[202:205], v141 offset:18432
	ds_read_b128 v[206:209], v141 offset:23040
	ds_read_b128 v[214:217], v140 offset:4608
	ds_read_b128 v[218:221], v140 offset:32
	ds_read_b128 v[222:225], v141 offset:18464
	ds_read_b128 v[226:229], v141 offset:23072
	ds_read_b128 v[230:233], v140 offset:4640
	s_waitcnt lgkmcnt(4)
	v_mfma_f32_32x32x16_bf16 v[50:65], v[198:201], v[202:205], v[50:65]
	v_mfma_f32_32x32x16_bf16 v[34:49], v[198:201], v[206:209], v[34:49]
	v_mfma_f32_32x32x16_bf16 v[18:33], v[214:217], v[202:205], v[18:33]
	v_mfma_f32_32x32x16_bf16 v[2:17], v[214:217], v[206:209], v[2:17]
	global_load_dwordx4 v[98:101], v[160:161], off offset:1024
	global_load_dwordx4 v[102:105], v[162:163], off offset:1024
	global_load_dwordx4 v[106:109], v[164:165], off offset:1024
	global_load_dwordx4 v[110:113], v[166:167], off offset:1024
	global_load_dwordx4 v[114:117], v[158:159], off offset:1024
	global_load_dwordx4 v[118:121], v[168:169], off offset:1024
	global_load_dwordx4 v[122:125], v[170:171], off offset:1024
	global_load_dwordx4 v[126:129], v[172:173], off offset:1024
	ds_read_b128 v[198:201], v140 offset:64
	ds_read_b128 v[202:205], v141 offset:18496
	ds_read_b128 v[206:209], v141 offset:23104
	ds_read_b128 v[214:217], v140 offset:4672
	s_waitcnt lgkmcnt(4)
	v_mfma_f32_32x32x16_bf16 v[50:65], v[218:221], v[222:225], v[50:65]
	v_mfma_f32_32x32x16_bf16 v[34:49], v[218:221], v[226:229], v[34:49]
	v_mfma_f32_32x32x16_bf16 v[18:33], v[230:233], v[222:225], v[18:33]
	v_mfma_f32_32x32x16_bf16 v[2:17], v[230:233], v[226:229], v[2:17]
	ds_read_b128 v[218:221], v140 offset:96
	ds_read_b128 v[222:225], v141 offset:18528
	ds_read_b128 v[226:229], v141 offset:23136
	ds_read_b128 v[230:233], v140 offset:4704
	s_waitcnt lgkmcnt(4)
	v_mfma_f32_32x32x16_bf16 v[50:65], v[198:201], v[202:205], v[50:65]
	v_mfma_f32_32x32x16_bf16 v[34:49], v[198:201], v[206:209], v[34:49]
	v_mfma_f32_32x32x16_bf16 v[18:33], v[214:217], v[202:205], v[18:33]
	v_mfma_f32_32x32x16_bf16 v[2:17], v[214:217], v[206:209], v[2:17]
	s_waitcnt lgkmcnt(0)
	v_mfma_f32_32x32x16_bf16 v[50:65], v[218:221], v[222:225], v[50:65]
	v_mfma_f32_32x32x16_bf16 v[34:49], v[218:221], v[226:229], v[34:49]
	v_mfma_f32_32x32x16_bf16 v[18:33], v[230:233], v[222:225], v[18:33]
	v_mfma_f32_32x32x16_bf16 v[2:17], v[230:233], v[226:229], v[2:17]
	s_setprio 0
	s_waitcnt vmcnt(8)
	ds_write_b128 v188, v[66:69] offset:36864
	ds_write_b128 v188, v[70:73] offset:41472
	ds_write_b128 v188, v[74:77] offset:46080
	ds_write_b128 v188, v[78:81] offset:50688
	ds_write_b128 v188, v[82:85] offset:55296
	ds_write_b128 v188, v[86:89] offset:59904
	ds_write_b128 v188, v[90:93] offset:64512
	ds_write_b128 v189, v[94:97] offset:13824
	s_waitcnt lgkmcnt(0)
	s_barrier
; __device__ __forceinline__ void gemm_kstep(const u16* sb, int wn, int wt, int r, int h, f32x16 (&acc)[2][2]) {
;   const u16* bw = sb + (wn * 64 + r) * LDT + h * 8;
;   const u16* bx = sb + TILE_U16 + (wt * 64 + r) * LDT + h * 8;
;   __builtin_amdgcn_s_setprio(1);
; #pragma unroll
;   for (int ks = 0; ks < 4; ++ks) {
;     bf16x8 a0 = *(const bf16x8*)(bw + ks * 16);
;     bf16x8 a1 = *(const bf16x8*)(bw + 32 * LDT + ks * 16);
;     bf16x8 b0 = *(const bf16x8*)(bx + ks * 16);
;     bf16x8 b1 = *(const bf16x8*)(bx + 32 * LDT + ks * 16);
;     acc[0][0] = mfma32(a0, b0, acc[0][0]);
;     acc[0][1] = mfma32(a0, b1, acc[0][1]);
;     acc[1][0] = mfma32(a1, b0, acc[1][0]);
;     acc[1][1] = mfma32(a1, b1, acc[1][1]);
;   }
;   __builtin_amdgcn_s_setprio(0);
; }
; __device__ void gemm_phase(const u16* __restrict__ Wb, int ldw, const u16* __restrict__ Xb, int ldx, int K,
;                            u16* __restrict__ outb, int ldo, int ntn, int ntiles, u16* lds) {
;     ...
;     for (int kt = 0; kt < nk; kt += 2) {
;       if (kt + 2 < nk) gs_load(B, gw, ldw, gx, ldx, (kt + 2) * 64);
;       else if (has_next) gs_load(B, gwn, ldw, gxn, ldx, 0);
;       gemm_kstep(lds, wn, wt, r, h, acc);
;       gs_store(A, lds + 2 * TILE_U16, lo);
;       __syncthreads();
;       if (kt + 3 < nk) gs_load(A, gw, ldw, gx, ldx, (kt + 3) * 64);
;       else if (has_next) gs_load(A, gwn, ldw, gxn, ldx, 64);
;       gemm_kstep(lds + 2 * TILE_U16, wn, wt, r, h, acc);
;       if (kt + 2 < nk) gs_store(B, lds, lo);
;       __syncthreads();
;     }
	s_setprio 1
	ds_read_b128 v[198:201], v140 offset:36864
	ds_read_b128 v[202:205], v141 offset:55296
	ds_read_b128 v[206:209], v141 offset:59904
	ds_read_b128 v[214:217], v140 offset:41472
	ds_read_b128 v[218:221], v140 offset:36896
	ds_read_b128 v[222:225], v141 offset:55328
	ds_read_b128 v[226:229], v141 offset:59936
	ds_read_b128 v[230:233], v140 offset:41504
	s_waitcnt lgkmcnt(4)
	v_mfma_f32_32x32x16_bf16 v[50:65], v[198:201], v[202:205], v[50:65]
	v_mfma_f32_32x32x16_bf16 v[34:49], v[198:201], v[206:209], v[34:49]
	v_mfma_f32_32x32x16_bf16 v[18:33], v[214:217], v[202:205], v[18:33]
	v_mfma_f32_32x32x16_bf16 v[2:17], v[214:217], v[206:209], v[2:17]
	global_load_dwordx4 v[66:69], v[160:161], off offset:1152
	global_load_dwordx4 v[70:73], v[162:163], off offset:1152
	global_load_dwordx4 v[74:77], v[164:165], off offset:1152
	global_load_dwordx4 v[78:81], v[166:167], off offset:1152
	global_load_dwordx4 v[82:85], v[158:159], off offset:1152
	global_load_dwordx4 v[86:89], v[168:169], off offset:1152
	global_load_dwordx4 v[90:93], v[170:171], off offset:1152
	global_load_dwordx4 v[94:97], v[172:173], off offset:1152
	ds_read_b128 v[198:201], v140 offset:36928
	ds_read_b128 v[202:205], v141 offset:55360
	ds_read_b128 v[206:209], v141 offset:59968
	ds_read_b128 v[214:217], v140 offset:41536
	s_waitcnt lgkmcnt(4)
	v_mfma_f32_32x32x16_bf16 v[50:65], v[218:221], v[222:225], v[50:65]
	v_mfma_f32_32x32x16_bf16 v[34:49], v[218:221], v[226:229], v[34:49]
	v_mfma_f32_32x32x16_bf16 v[18:33], v[230:233], v[222:225], v[18:33]
	v_mfma_f32_32x32x16_bf16 v[2:17], v[230:233], v[226:229], v[2:17]
	ds_read_b128 v[218:221], v140 offset:36960
	ds_read_b128 v[222:225], v141 offset:55392
	ds_read_b128 v[226:229], v141 offset:60000
	ds_read_b128 v[230:233], v140 offset:41568
	s_waitcnt lgkmcnt(4)
	v_mfma_f32_32x32x16_bf16 v[50:65], v[198:201], v[202:205], v[50:65]
	v_mfma_f32_32x32x16_bf16 v[34:49], v[198:201], v[206:209], v[34:49]
	v_mfma_f32_32x32x16_bf16 v[18:33], v[214:217], v[202:205], v[18:33]
	v_mfma_f32_32x32x16_bf16 v[2:17], v[214:217], v[206:209], v[2:17]
	s_waitcnt lgkmcnt(0)
	v_mfma_f32_32x32x16_bf16 v[50:65], v[218:221], v[222:225], v[50:65]
	v_mfma_f32_32x32x16_bf16 v[34:49], v[218:221], v[226:229], v[34:49]
	v_mfma_f32_32x32x16_bf16 v[18:33], v[230:233], v[222:225], v[18:33]
	v_mfma_f32_32x32x16_bf16 v[2:17], v[230:233], v[226:229], v[2:17]
	s_setprio 0
	s_waitcnt vmcnt(8)
	ds_write_b128 v188, v[98:101]
	ds_write_b128 v188, v[102:105] offset:4608
	ds_write_b128 v188, v[106:109] offset:9216
	ds_write_b128 v188, v[110:113] offset:13824
	ds_write_b128 v188, v[114:117] offset:18432
	ds_write_b128 v188, v[118:121] offset:23040
	ds_write_b128 v188, v[122:125] offset:27648
	ds_write_b128 v188, v[126:129] offset:32256
	s_waitcnt lgkmcnt(0)
	s_barrier
	s_setprio 1
	ds_read_b128 v[198:201], v140
	ds_read_b128 v[202:205], v141 offset:18432
	ds_read_b128 v[206:209], v141 offset:23040
	ds_read_b128 v[214:217], v140 offset:4608
	ds_read_b128 v[218:221], v140 offset:32
	ds_read_b128 v[222:225], v141 offset:18464
	ds_read_b128 v[226:229], v141 offset:23072
	ds_read_b128 v[230:233], v140 offset:4640
	s_waitcnt lgkmcnt(4)
	v_mfma_f32_32x32x16_bf16 v[50:65], v[198:201], v[202:205], v[50:65]
	v_mfma_f32_32x32x16_bf16 v[34:49], v[198:201], v[206:209], v[34:49]
	v_mfma_f32_32x32x16_bf16 v[18:33], v[214:217], v[202:205], v[18:33]
	v_mfma_f32_32x32x16_bf16 v[2:17], v[214:217], v[206:209], v[2:17]
	global_load_dwordx4 v[98:101], v[160:161], off offset:1280
	global_load_dwordx4 v[102:105], v[162:163], off offset:1280
	global_load_dwordx4 v[106:109], v[164:165], off offset:1280
	global_load_dwordx4 v[110:113], v[166:167], off offset:1280
	global_load_dwordx4 v[114:117], v[158:159], off offset:1280
	global_load_dwordx4 v[118:121], v[168:169], off offset:1280
	global_load_dwordx4 v[122:125], v[170:171], off offset:1280
	global_load_dwordx4 v[126:129], v[172:173], off offset:1280
	ds_read_b128 v[198:201], v140 offset:64
	ds_read_b128 v[202:205], v141 offset:18496
	ds_read_b128 v[206:209], v141 offset:23104
	ds_read_b128 v[214:217], v140 offset:4672
	s_waitcnt lgkmcnt(4)
	v_mfma_f32_32x32x16_bf16 v[50:65], v[218:221], v[222:225], v[50:65]
	v_mfma_f32_32x32x16_bf16 v[34:49], v[218:221], v[226:229], v[34:49]
	v_mfma_f32_32x32x16_bf16 v[18:33], v[230:233], v[222:225], v[18:33]
	v_mfma_f32_32x32x16_bf16 v[2:17], v[230:233], v[226:229], v[2:17]
	ds_read_b128 v[218:221], v140 offset:96
	ds_read_b128 v[222:225], v141 offset:18528
	ds_read_b128 v[226:229], v141 offset:23136
	ds_read_b128 v[230:233], v140 offset:4704
	s_waitcnt lgkmcnt(4)
	v_mfma_f32_32x32x16_bf16 v[50:65], v[198:201], v[202:205], v[50:65]
	v_mfma_f32_32x32x16_bf16 v[34:49], v[198:201], v[206:209], v[34:49]
	v_mfma_f32_32x32x16_bf16 v[18:33], v[214:217], v[202:205], v[18:33]
	v_mfma_f32_32x32x16_bf16 v[2:17], v[214:217], v[206:209], v[2:17]
	s_waitcnt lgkmcnt(0)
	v_mfma_f32_32x32x16_bf16 v[50:65], v[218:221], v[222:225], v[50:65]
	v_mfma_f32_32x32x16_bf16 v[34:49], v[218:221], v[226:229], v[34:49]
	v_mfma_f32_32x32x16_bf16 v[18:33], v[230:233], v[222:225], v[18:33]
	v_mfma_f32_32x32x16_bf16 v[2:17], v[230:233], v[226:229], v[2:17]
	s_setprio 0
	s_waitcnt vmcnt(8)
	ds_write_b128 v188, v[66:69] offset:36864
	ds_write_b128 v188, v[70:73] offset:41472
	ds_write_b128 v188, v[74:77] offset:46080
	ds_write_b128 v188, v[78:81] offset:50688
	ds_write_b128 v188, v[82:85] offset:55296
	ds_write_b128 v188, v[86:89] offset:59904
	ds_write_b128 v188, v[90:93] offset:64512
	ds_write_b128 v189, v[94:97] offset:13824
	s_waitcnt lgkmcnt(0)
	s_barrier
; __device__ __forceinline__ void gemm_kstep(const u16* sb, int wn, int wt, int r, int h, f32x16 (&acc)[2][2]) {
;   const u16* bw = sb + (wn * 64 + r) * LDT + h * 8;
;   const u16* bx = sb + TILE_U16 + (wt * 64 + r) * LDT + h * 8;
;   __builtin_amdgcn_s_setprio(1);
; #pragma unroll
;   for (int ks = 0; ks < 4; ++ks) {
;     bf16x8 a0 = *(const bf16x8*)(bw + ks * 16);
;     bf16x8 a1 = *(const bf16x8*)(bw + 32 * LDT + ks * 16);
;     bf16x8 b0 = *(const bf16x8*)(bx + ks * 16);
;     bf16x8 b1 = *(const bf16x8*)(bx + 32 * LDT + ks * 16);
;     acc[0][0] = mfma32(a0, b0, acc[0][0]);
;     acc[0][1] = mfma32(a0, b1, acc[0][1]);
;     acc[1][0] = mfma32(a1, b0, acc[1][0]);
;     acc[1][1] = mfma32(a1, b1, acc[1][1]);
;   }
;   __builtin_amdgcn_s_setprio(0);
; }
; __device__ void gemm_phase(const u16* __restrict__ Wb, int ldw, const u16* __restrict__ Xb, int ldx, int K,
;                            u16* __restrict__ outb, int ldo, int ntn, int ntiles, u16* lds) {
;     ...
;     for (int kt = 0; kt < nk; kt += 2) {
;       if (kt + 2 < nk) gs_load(B, gw, ldw, gx, ldx, (kt + 2) * 64);
;       else if (has_next) gs_load(B, gwn, ldw, gxn, ldx, 0);
;       gemm_kstep(lds, wn, wt, r, h, acc);
;       gs_store(A, lds + 2 * TILE_U16, lo);
;       __syncthreads();
;       if (kt + 3 < nk) gs_load(A, gw, ldw, gx, ldx, (kt + 3) * 64);
;       else if (has_next) gs_load(A, gwn, ldw, gxn, ldx, 64);
;       gemm_kstep(lds + 2 * TILE_U16, wn, wt, r, h, acc);
;       if (kt + 2 < nk) gs_store(B, lds, lo);
;       __syncthreads();
;     }
	s_setprio 1
	ds_read_b128 v[198:201], v140 offset:36864
	ds_read_b128 v[202:205], v141 offset:55296
	ds_read_b128 v[206:209], v141 offset:59904
	ds_read_b128 v[214:217], v140 offset:41472
	ds_read_b128 v[218:221], v140 offset:36896
	ds_read_b128 v[222:225], v141 offset:55328
	ds_read_b128 v[226:229], v141 offset:59936
	ds_read_b128 v[230:233], v140 offset:41504
	s_waitcnt lgkmcnt(4)
	v_mfma_f32_32x32x16_bf16 v[50:65], v[198:201], v[202:205], v[50:65]
	v_mfma_f32_32x32x16_bf16 v[34:49], v[198:201], v[206:209], v[34:49]
	v_mfma_f32_32x32x16_bf16 v[18:33], v[214:217], v[202:205], v[18:33]
	v_mfma_f32_32x32x16_bf16 v[2:17], v[214:217], v[206:209], v[2:17]
	global_load_dwordx4 v[66:69], v[160:161], off offset:1408
	global_load_dwordx4 v[70:73], v[162:163], off offset:1408
	global_load_dwordx4 v[74:77], v[164:165], off offset:1408
	global_load_dwordx4 v[78:81], v[166:167], off offset:1408
	global_load_dwordx4 v[82:85], v[158:159], off offset:1408
	global_load_dwordx4 v[86:89], v[168:169], off offset:1408
	global_load_dwordx4 v[90:93], v[170:171], off offset:1408
	global_load_dwordx4 v[94:97], v[172:173], off offset:1408
	ds_read_b128 v[198:201], v140 offset:36928
	ds_read_b128 v[202:205], v141 offset:55360
	ds_read_b128 v[206:209], v141 offset:59968
	ds_read_b128 v[214:217], v140 offset:41536
	s_waitcnt lgkmcnt(4)
	v_mfma_f32_32x32x16_bf16 v[50:65], v[218:221], v[222:225], v[50:65]
	v_mfma_f32_32x32x16_bf16 v[34:49], v[218:221], v[226:229], v[34:49]
	v_mfma_f32_32x32x16_bf16 v[18:33], v[230:233], v[222:225], v[18:33]
	v_mfma_f32_32x32x16_bf16 v[2:17], v[230:233], v[226:229], v[2:17]
	ds_read_b128 v[218:221], v140 offset:36960
	ds_read_b128 v[222:225], v141 offset:55392
	ds_read_b128 v[226:229], v141 offset:60000
	ds_read_b128 v[230:233], v140 offset:41568
	s_waitcnt lgkmcnt(4)
	v_mfma_f32_32x32x16_bf16 v[50:65], v[198:201], v[202:205], v[50:65]
	v_mfma_f32_32x32x16_bf16 v[34:49], v[198:201], v[206:209], v[34:49]
	v_mfma_f32_32x32x16_bf16 v[18:33], v[214:217], v[202:205], v[18:33]
	v_mfma_f32_32x32x16_bf16 v[2:17], v[214:217], v[206:209], v[2:17]
	s_waitcnt lgkmcnt(0)
	v_mfma_f32_32x32x16_bf16 v[50:65], v[218:221], v[222:225], v[50:65]
	v_mfma_f32_32x32x16_bf16 v[34:49], v[218:221], v[226:229], v[34:49]
	v_mfma_f32_32x32x16_bf16 v[18:33], v[230:233], v[222:225], v[18:33]
	v_mfma_f32_32x32x16_bf16 v[2:17], v[230:233], v[226:229], v[2:17]
	s_setprio 0
	s_waitcnt vmcnt(8)
	ds_write_b128 v188, v[98:101]
	ds_write_b128 v188, v[102:105] offset:4608
	ds_write_b128 v188, v[106:109] offset:9216
	ds_write_b128 v188, v[110:113] offset:13824
	ds_write_b128 v188, v[114:117] offset:18432
	ds_write_b128 v188, v[118:121] offset:23040
	ds_write_b128 v188, v[122:125] offset:27648
	ds_write_b128 v188, v[126:129] offset:32256
	s_waitcnt lgkmcnt(0)
	s_barrier
	s_setprio 1
	ds_read_b128 v[198:201], v140
	ds_read_b128 v[202:205], v141 offset:18432
	ds_read_b128 v[206:209], v141 offset:23040
	ds_read_b128 v[214:217], v140 offset:4608
	ds_read_b128 v[218:221], v140 offset:32
	ds_read_b128 v[222:225], v141 offset:18464
	ds_read_b128 v[226:229], v141 offset:23072
	ds_read_b128 v[230:233], v140 offset:4640
	s_waitcnt lgkmcnt(4)
	v_mfma_f32_32x32x16_bf16 v[50:65], v[198:201], v[202:205], v[50:65]
	v_mfma_f32_32x32x16_bf16 v[34:49], v[198:201], v[206:209], v[34:49]
	v_mfma_f32_32x32x16_bf16 v[18:33], v[214:217], v[202:205], v[18:33]
	v_mfma_f32_32x32x16_bf16 v[2:17], v[214:217], v[206:209], v[2:17]
	global_load_dwordx4 v[98:101], v[160:161], off offset:1536
	global_load_dwordx4 v[102:105], v[162:163], off offset:1536
	global_load_dwordx4 v[106:109], v[164:165], off offset:1536
	global_load_dwordx4 v[110:113], v[166:167], off offset:1536
	global_load_dwordx4 v[114:117], v[158:159], off offset:1536
	global_load_dwordx4 v[118:121], v[168:169], off offset:1536
	global_load_dwordx4 v[122:125], v[170:171], off offset:1536
	global_load_dwordx4 v[126:129], v[172:173], off offset:1536
	ds_read_b128 v[198:201], v140 offset:64
	ds_read_b128 v[202:205], v141 offset:18496
	ds_read_b128 v[206:209], v141 offset:23104
	ds_read_b128 v[214:217], v140 offset:4672
	s_waitcnt lgkmcnt(4)
	v_mfma_f32_32x32x16_bf16 v[50:65], v[218:221], v[222:225], v[50:65]
	v_mfma_f32_32x32x16_bf16 v[34:49], v[218:221], v[226:229], v[34:49]
	v_mfma_f32_32x32x16_bf16 v[18:33], v[230:233], v[222:225], v[18:33]
	v_mfma_f32_32x32x16_bf16 v[2:17], v[230:233], v[226:229], v[2:17]
	ds_read_b128 v[218:221], v140 offset:96
	ds_read_b128 v[222:225], v141 offset:18528
	ds_read_b128 v[226:229], v141 offset:23136
	ds_read_b128 v[230:233], v140 offset:4704
	s_waitcnt lgkmcnt(4)
	v_mfma_f32_32x32x16_bf16 v[50:65], v[198:201], v[202:205], v[50:65]
	v_mfma_f32_32x32x16_bf16 v[34:49], v[198:201], v[206:209], v[34:49]
	v_mfma_f32_32x32x16_bf16 v[18:33], v[214:217], v[202:205], v[18:33]
	v_mfma_f32_32x32x16_bf16 v[2:17], v[214:217], v[206:209], v[2:17]
	s_waitcnt lgkmcnt(0)
	v_mfma_f32_32x32x16_bf16 v[50:65], v[218:221], v[222:225], v[50:65]
	v_mfma_f32_32x32x16_bf16 v[34:49], v[218:221], v[226:229], v[34:49]
	v_mfma_f32_32x32x16_bf16 v[18:33], v[230:233], v[222:225], v[18:33]
	v_mfma_f32_32x32x16_bf16 v[2:17], v[230:233], v[226:229], v[2:17]
	s_setprio 0
	s_waitcnt vmcnt(8)
	ds_write_b128 v188, v[66:69] offset:36864
	ds_write_b128 v188, v[70:73] offset:41472
	ds_write_b128 v188, v[74:77] offset:46080
	ds_write_b128 v188, v[78:81] offset:50688
	ds_write_b128 v188, v[82:85] offset:55296
	ds_write_b128 v188, v[86:89] offset:59904
	ds_write_b128 v188, v[90:93] offset:64512
	ds_write_b128 v189, v[94:97] offset:13824
	s_waitcnt lgkmcnt(0)
	s_barrier
; __device__ __forceinline__ void gemm_kstep(const u16* sb, int wn, int wt, int r, int h, f32x16 (&acc)[2][2]) {
;   const u16* bw = sb + (wn * 64 + r) * LDT + h * 8;
;   const u16* bx = sb + TILE_U16 + (wt * 64 + r) * LDT + h * 8;
;   __builtin_amdgcn_s_setprio(1);
; #pragma unroll
;   for (int ks = 0; ks < 4; ++ks) {
;     bf16x8 a0 = *(const bf16x8*)(bw + ks * 16);
;     bf16x8 a1 = *(const bf16x8*)(bw + 32 * LDT + ks * 16);
;     bf16x8 b0 = *(const bf16x8*)(bx + ks * 16);
;     bf16x8 b1 = *(const bf16x8*)(bx + 32 * LDT + ks * 16);
;     acc[0][0] = mfma32(a0, b0, acc[0][0]);
;     acc[0][1] = mfma32(a0, b1, acc[0][1]);
;     acc[1][0] = mfma32(a1, b0, acc[1][0]);
;     acc[1][1] = mfma32(a1, b1, acc[1][1]);
;   }
;   __builtin_amdgcn_s_setprio(0);
; }
; __device__ void gemm_phase(const u16* __restrict__ Wb, int ldw, const u16* __restrict__ Xb, int ldx, int K,
;                            u16* __restrict__ outb, int ldo, int ntn, int ntiles, u16* lds) {
;     ...
;     for (int kt = 0; kt < nk; kt += 2) {
;       if (kt + 2 < nk) gs_load(B, gw, ldw, gx, ldx, (kt + 2) * 64);
;       else if (has_next) gs_load(B, gwn, ldw, gxn, ldx, 0);
;       gemm_kstep(lds, wn, wt, r, h, acc);
;       gs_store(A, lds + 2 * TILE_U16, lo);
;       __syncthreads();
;       if (kt + 3 < nk) gs_load(A, gw, ldw, gx, ldx, (kt + 3) * 64);
;       else if (has_next) gs_load(A, gwn, ldw, gxn, ldx, 64);
;       gemm_kstep(lds + 2 * TILE_U16, wn, wt, r, h, acc);
;       if (kt + 2 < nk) gs_store(B, lds, lo);
;       __syncthreads();
;     }
	s_setprio 1
	ds_read_b128 v[198:201], v140 offset:36864
	ds_read_b128 v[202:205], v141 offset:55296
	ds_read_b128 v[206:209], v141 offset:59904
	ds_read_b128 v[214:217], v140 offset:41472
	ds_read_b128 v[218:221], v140 offset:36896
	ds_read_b128 v[222:225], v141 offset:55328
	ds_read_b128 v[226:229], v141 offset:59936
	ds_read_b128 v[230:233], v140 offset:41504
	s_waitcnt lgkmcnt(4)
	v_mfma_f32_32x32x16_bf16 v[50:65], v[198:201], v[202:205], v[50:65]
	v_mfma_f32_32x32x16_bf16 v[34:49], v[198:201], v[206:209], v[34:49]
	v_mfma_f32_32x32x16_bf16 v[18:33], v[214:217], v[202:205], v[18:33]
	v_mfma_f32_32x32x16_bf16 v[2:17], v[214:217], v[206:209], v[2:17]
	global_load_dwordx4 v[66:69], v[160:161], off offset:1664
	global_load_dwordx4 v[70:73], v[162:163], off offset:1664
	global_load_dwordx4 v[74:77], v[164:165], off offset:1664
	global_load_dwordx4 v[78:81], v[166:167], off offset:1664
	global_load_dwordx4 v[82:85], v[158:159], off offset:1664
	global_load_dwordx4 v[86:89], v[168:169], off offset:1664
	global_load_dwordx4 v[90:93], v[170:171], off offset:1664
	global_load_dwordx4 v[94:97], v[172:173], off offset:1664
	ds_read_b128 v[198:201], v140 offset:36928
	ds_read_b128 v[202:205], v141 offset:55360
	ds_read_b128 v[206:209], v141 offset:59968
	ds_read_b128 v[214:217], v140 offset:41536
	s_waitcnt lgkmcnt(4)
	v_mfma_f32_32x32x16_bf16 v[50:65], v[218:221], v[222:225], v[50:65]
	v_mfma_f32_32x32x16_bf16 v[34:49], v[218:221], v[226:229], v[34:49]
	v_mfma_f32_32x32x16_bf16 v[18:33], v[230:233], v[222:225], v[18:33]
	v_mfma_f32_32x32x16_bf16 v[2:17], v[230:233], v[226:229], v[2:17]
	ds_read_b128 v[218:221], v140 offset:36960
	ds_read_b128 v[222:225], v141 offset:55392
	ds_read_b128 v[226:229], v141 offset:60000
	ds_read_b128 v[230:233], v140 offset:41568
	s_waitcnt lgkmcnt(4)
	v_mfma_f32_32x32x16_bf16 v[50:65], v[198:201], v[202:205], v[50:65]
	v_mfma_f32_32x32x16_bf16 v[34:49], v[198:201], v[206:209], v[34:49]
	v_mfma_f32_32x32x16_bf16 v[18:33], v[214:217], v[202:205], v[18:33]
	v_mfma_f32_32x32x16_bf16 v[2:17], v[214:217], v[206:209], v[2:17]
	s_waitcnt lgkmcnt(0)
	v_mfma_f32_32x32x16_bf16 v[50:65], v[218:221], v[222:225], v[50:65]
	v_mfma_f32_32x32x16_bf16 v[34:49], v[218:221], v[226:229], v[34:49]
	v_mfma_f32_32x32x16_bf16 v[18:33], v[230:233], v[222:225], v[18:33]
	v_mfma_f32_32x32x16_bf16 v[2:17], v[230:233], v[226:229], v[2:17]
	s_setprio 0
	s_waitcnt vmcnt(8)
	ds_write_b128 v188, v[98:101]
	ds_write_b128 v188, v[102:105] offset:4608
	ds_write_b128 v188, v[106:109] offset:9216
	ds_write_b128 v188, v[110:113] offset:13824
	ds_write_b128 v188, v[114:117] offset:18432
	ds_write_b128 v188, v[118:121] offset:23040
	ds_write_b128 v188, v[122:125] offset:27648
	ds_write_b128 v188, v[126:129] offset:32256
	s_waitcnt lgkmcnt(0)
	s_barrier
	s_setprio 1
	ds_read_b128 v[198:201], v140
	ds_read_b128 v[202:205], v141 offset:18432
	ds_read_b128 v[206:209], v141 offset:23040
	ds_read_b128 v[214:217], v140 offset:4608
	ds_read_b128 v[218:221], v140 offset:32
	ds_read_b128 v[222:225], v141 offset:18464
	ds_read_b128 v[226:229], v141 offset:23072
	ds_read_b128 v[230:233], v140 offset:4640
	s_waitcnt lgkmcnt(4)
	v_mfma_f32_32x32x16_bf16 v[50:65], v[198:201], v[202:205], v[50:65]
	v_mfma_f32_32x32x16_bf16 v[34:49], v[198:201], v[206:209], v[34:49]
	v_mfma_f32_32x32x16_bf16 v[18:33], v[214:217], v[202:205], v[18:33]
	v_mfma_f32_32x32x16_bf16 v[2:17], v[214:217], v[206:209], v[2:17]
	global_load_dwordx4 v[98:101], v[160:161], off offset:1792
	global_load_dwordx4 v[102:105], v[162:163], off offset:1792
	global_load_dwordx4 v[106:109], v[164:165], off offset:1792
	global_load_dwordx4 v[110:113], v[166:167], off offset:1792
	global_load_dwordx4 v[114:117], v[158:159], off offset:1792
	global_load_dwordx4 v[118:121], v[168:169], off offset:1792
	global_load_dwordx4 v[122:125], v[170:171], off offset:1792
	global_load_dwordx4 v[126:129], v[172:173], off offset:1792
	ds_read_b128 v[198:201], v140 offset:64
	ds_read_b128 v[202:205], v141 offset:18496
	ds_read_b128 v[206:209], v141 offset:23104
	ds_read_b128 v[214:217], v140 offset:4672
	s_waitcnt lgkmcnt(4)
	v_mfma_f32_32x32x16_bf16 v[50:65], v[218:221], v[222:225], v[50:65]
	v_mfma_f32_32x32x16_bf16 v[34:49], v[218:221], v[226:229], v[34:49]
	v_mfma_f32_32x32x16_bf16 v[18:33], v[230:233], v[222:225], v[18:33]
	v_mfma_f32_32x32x16_bf16 v[2:17], v[230:233], v[226:229], v[2:17]
	ds_read_b128 v[218:221], v140 offset:96
	ds_read_b128 v[222:225], v141 offset:18528
	ds_read_b128 v[226:229], v141 offset:23136
	ds_read_b128 v[230:233], v140 offset:4704
	s_waitcnt lgkmcnt(4)
	v_mfma_f32_32x32x16_bf16 v[50:65], v[198:201], v[202:205], v[50:65]
	v_mfma_f32_32x32x16_bf16 v[34:49], v[198:201], v[206:209], v[34:49]
	v_mfma_f32_32x32x16_bf16 v[18:33], v[214:217], v[202:205], v[18:33]
	v_mfma_f32_32x32x16_bf16 v[2:17], v[214:217], v[206:209], v[2:17]
	s_waitcnt lgkmcnt(0)
	v_mfma_f32_32x32x16_bf16 v[50:65], v[218:221], v[222:225], v[50:65]
	v_mfma_f32_32x32x16_bf16 v[34:49], v[218:221], v[226:229], v[34:49]
	v_mfma_f32_32x32x16_bf16 v[18:33], v[230:233], v[222:225], v[18:33]
	v_mfma_f32_32x32x16_bf16 v[2:17], v[230:233], v[226:229], v[2:17]
	s_setprio 0
	s_waitcnt vmcnt(8)
	ds_write_b128 v188, v[66:69] offset:36864
	ds_write_b128 v188, v[70:73] offset:41472
	ds_write_b128 v188, v[74:77] offset:46080
	ds_write_b128 v188, v[78:81] offset:50688
	ds_write_b128 v188, v[82:85] offset:55296
	ds_write_b128 v188, v[86:89] offset:59904
	ds_write_b128 v188, v[90:93] offset:64512
	ds_write_b128 v189, v[94:97] offset:13824
	s_waitcnt lgkmcnt(0)
	s_barrier
; __device__ __forceinline__ void gemm_kstep(const u16* sb, int wn, int wt, int r, int h, f32x16 (&acc)[2][2]) {
;   const u16* bw = sb + (wn * 64 + r) * LDT + h * 8;
;   const u16* bx = sb + TILE_U16 + (wt * 64 + r) * LDT + h * 8;
;   __builtin_amdgcn_s_setprio(1);
; #pragma unroll
;   for (int ks = 0; ks < 4; ++ks) {
;     bf16x8 a0 = *(const bf16x8*)(bw + ks * 16);
;     bf16x8 a1 = *(const bf16x8*)(bw + 32 * LDT + ks * 16);
;     bf16x8 b0 = *(const bf16x8*)(bx + ks * 16);
;     bf16x8 b1 = *(const bf16x8*)(bx + 32 * LDT + ks * 16);
;     acc[0][0] = mfma32(a0, b0, acc[0][0]);
;     acc[0][1] = mfma32(a0, b1, acc[0][1]);
;     acc[1][0] = mfma32(a1, b0, acc[1][0]);
;     acc[1][1] = mfma32(a1, b1, acc[1][1]);
;   }
;   __builtin_amdgcn_s_setprio(0);
; }
; __device__ void gemm_phase(const u16* __restrict__ Wb, int ldw, const u16* __restrict__ Xb, int ldx, int K,
;                            u16* __restrict__ outb, int ldo, int ntn, int ntiles, u16* lds) {
;     ...
;     for (int kt = 0; kt < nk; kt += 2) {
;       if (kt + 2 < nk) gs_load(B, gw, ldw, gx, ldx, (kt + 2) * 64);
;       else if (has_next) gs_load(B, gwn, ldw, gxn, ldx, 0);
;       gemm_kstep(lds, wn, wt, r, h, acc);
;       gs_store(A, lds + 2 * TILE_U16, lo);
;       __syncthreads();
;       if (kt + 3 < nk) gs_load(A, gw, ldw, gx, ldx, (kt + 3) * 64);
;       else if (has_next) gs_load(A, gwn, ldw, gxn, ldx, 64);
;       gemm_kstep(lds + 2 * TILE_U16, wn, wt, r, h, acc);
;       if (kt + 2 < nk) gs_store(B, lds, lo);
;       __syncthreads();
;     }
	global_load_dwordx4 v[66:69], v[160:161], off offset:1920
	global_load_dwordx4 v[70:73], v[162:163], off offset:1920
	global_load_dwordx4 v[74:77], v[164:165], off offset:1920
	global_load_dwordx4 v[78:81], v[166:167], off offset:1920
	global_load_dwordx4 v[82:85], v[158:159], off offset:1920
	global_load_dwordx4 v[86:89], v[168:169], off offset:1920
	global_load_dwordx4 v[90:93], v[170:171], off offset:1920
	global_load_dwordx4 v[94:97], v[172:173], off offset:1920
	s_setprio 1
	ds_read_b128 v[158:161], v140 offset:36864
	ds_read_b128 v[162:165], v141 offset:55296
	ds_read_b128 v[166:169], v141 offset:59904
	ds_read_b128 v[214:217], v140 offset:41472
	ds_read_b128 v[218:221], v140 offset:36896
	ds_read_b128 v[222:225], v141 offset:55328
	ds_read_b128 v[226:229], v141 offset:59936
	ds_read_b128 v[230:233], v140 offset:41504
	s_waitcnt lgkmcnt(4)
	v_mfma_f32_32x32x16_bf16 v[50:65], v[158:161], v[162:165], v[50:65]
	v_mfma_f32_32x32x16_bf16 v[34:49], v[158:161], v[166:169], v[34:49]
	v_mfma_f32_32x32x16_bf16 v[18:33], v[214:217], v[162:165], v[18:33]
	v_mfma_f32_32x32x16_bf16 v[2:17], v[214:217], v[166:169], v[2:17]
	ds_read_b128 v[158:161], v140 offset:36928
	ds_read_b128 v[162:165], v141 offset:55360
	ds_read_b128 v[166:169], v141 offset:59968
	ds_read_b128 v[214:217], v140 offset:41536
	s_waitcnt lgkmcnt(4)
	v_mfma_f32_32x32x16_bf16 v[50:65], v[218:221], v[222:225], v[50:65]
	v_mfma_f32_32x32x16_bf16 v[34:49], v[218:221], v[226:229], v[34:49]
	v_mfma_f32_32x32x16_bf16 v[18:33], v[230:233], v[222:225], v[18:33]
	v_mfma_f32_32x32x16_bf16 v[2:17], v[230:233], v[226:229], v[2:17]
	ds_read_b128 v[218:221], v140 offset:36960
	ds_read_b128 v[222:225], v141 offset:55392
	ds_read_b128 v[226:229], v141 offset:60000
	ds_read_b128 v[230:233], v140 offset:41568
	s_waitcnt lgkmcnt(4)
	v_mfma_f32_32x32x16_bf16 v[50:65], v[158:161], v[162:165], v[50:65]
	v_mfma_f32_32x32x16_bf16 v[34:49], v[158:161], v[166:169], v[34:49]
	v_mfma_f32_32x32x16_bf16 v[18:33], v[214:217], v[162:165], v[18:33]
	v_mfma_f32_32x32x16_bf16 v[2:17], v[214:217], v[166:169], v[2:17]
	s_waitcnt lgkmcnt(0)
	v_mfma_f32_32x32x16_bf16 v[50:65], v[218:221], v[222:225], v[50:65]
	v_mfma_f32_32x32x16_bf16 v[34:49], v[218:221], v[226:229], v[34:49]
	v_mfma_f32_32x32x16_bf16 v[18:33], v[230:233], v[222:225], v[18:33]
	v_mfma_f32_32x32x16_bf16 v[2:17], v[230:233], v[226:229], v[2:17]
	s_setprio 0
	s_and_b64 vcc, exec, s[16:17]
	s_waitcnt vmcnt(8)
	ds_write_b128 v188, v[98:101]
	ds_write_b128 v188, v[102:105] offset:4608
	ds_write_b128 v188, v[106:109] offset:9216
	ds_write_b128 v188, v[110:113] offset:13824
	ds_write_b128 v188, v[114:117] offset:18432
	ds_write_b128 v188, v[118:121] offset:23040
	ds_write_b128 v188, v[122:125] offset:27648
	ds_write_b128 v188, v[126:129] offset:32256
	s_waitcnt lgkmcnt(0)
	s_barrier
	s_cbranch_vccnz .LBB0_600
	v_add_co_u32_e32 v102, vcc, 0x10000, v132
	global_load_dwordx4 v[98:101], v[132:133], off
	s_nop 0
	v_addc_co_u32_e32 v103, vcc, 0, v133, vcc
	v_add_co_u32_e32 v106, vcc, 0x20000, v132
	s_nop 1
	v_addc_co_u32_e32 v107, vcc, 0, v133, vcc
	v_add_co_u32_e32 v110, vcc, 0x30000, v132
	global_load_dwordx4 v[102:105], v[102:103], off
	s_nop 0
	global_load_dwordx4 v[106:109], v[106:107], off
	v_addc_co_u32_e32 v111, vcc, 0, v133, vcc
	v_add_co_u32_e32 v118, vcc, 0x10000, v134
	global_load_dwordx4 v[110:113], v[110:111], off
	s_nop 0
	global_load_dwordx4 v[114:117], v[134:135], off
	v_addc_co_u32_e32 v119, vcc, 0, v135, vcc
	v_add_co_u32_e32 v122, vcc, 0x20000, v134
	s_nop 1
	v_addc_co_u32_e32 v123, vcc, 0, v135, vcc
	v_add_co_u32_e32 v126, vcc, 0x30000, v134
	global_load_dwordx4 v[118:121], v[118:119], off
	s_nop 0
	global_load_dwordx4 v[122:125], v[122:123], off
	v_addc_co_u32_e32 v127, vcc, 0, v135, vcc
	global_load_dwordx4 v[126:129], v[126:127], off

; __device__ __forceinline__ void gemm_kstep(const u16* sb, int wn, int wt, int r, int h, f32x16 (&acc)[2][2]) {
;   const u16* bw = sb + (wn * 64 + r) * LDT + h * 8;
;   const u16* bx = sb + TILE_U16 + (wt * 64 + r) * LDT + h * 8;
;   __builtin_amdgcn_s_setprio(1);
; #pragma unroll
;   for (int ks = 0; ks < 4; ++ks) {
;     bf16x8 a0 = *(const bf16x8*)(bw + ks * 16);
;     bf16x8 a1 = *(const bf16x8*)(bw + 32 * LDT + ks * 16);
;     bf16x8 b0 = *(const bf16x8*)(bx + ks * 16);
;     bf16x8 b1 = *(const bf16x8*)(bx + 32 * LDT + ks * 16);
;     acc[0][0] = mfma32(a0, b0, acc[0][0]);
;     acc[0][1] = mfma32(a0, b1, acc[0][1]);
;     acc[1][0] = mfma32(a1, b0, acc[1][0]);
;     acc[1][1] = mfma32(a1, b1, acc[1][1]);
;   }
;   __builtin_amdgcn_s_setprio(0);
; }
; __device__ void gemm_phase(const u16* __restrict__ Wb, int ldw, const u16* __restrict__ Xb, int ldx, int K,
;                            u16* __restrict__ outb, int ldo, int ntn, int ntiles, u16* lds) {
;     ...
;   for (; q < L; q += nbl) {
;     const int qn = q + nbl;
;     const bool has_next = qn < L;
;     const int qq = has_next ? qn : q;
;     const u16* gwn = Wb + (size_t)(GP_NT(qq) * 128 + lrow) * ldw + lc * 8;
;     const u16* gxn = Xb + (size_t)(GP_MT(qq) * 128 + lrow) * ldx + lc * 8;
;     f32x16 acc[2][2];
; #pragma unroll
;     for (int a = 0; a < 2; ++a)
; #pragma unroll
;       for (int b = 0; b < 2; ++b)
; #pragma unroll
;         for (int i = 0; i < 16; ++i) acc[a][b][i] = 0.f;
;     gs_store(B, lds, lo);
;     __syncthreads();
;     for (int kt = 0; kt < nk; kt += 2) {
;       if (kt + 2 < nk) gs_load(B, gw, ldw, gx, ldx, (kt + 2) * 64);
;       else if (has_next) gs_load(B, gwn, ldw, gxn, ldx, 0);
;       gemm_kstep(lds, wn, wt, r, h, acc);
;       gs_store(A, lds + 2 * TILE_U16, lo);
;       __syncthreads();
.LBB0_609:
	v_mov_b64_e32 v[160:161], v[132:133]
	v_add_co_u32_e32 v162, vcc, s81, v160
	v_mov_b64_e32 v[158:159], v[134:135]
	s_nop 0
	v_addc_co_u32_e32 v163, vcc, 0, v161, vcc
	v_add_co_u32_e32 v164, vcc, s80, v160
	s_waitcnt vmcnt(1)
	ds_write_b128 v188, v[86:89]
	ds_write_b128 v188, v[98:101] offset:4608
	ds_write_b128 v188, v[102:105] offset:9216
	ds_write_b128 v188, v[110:113] offset:13824
	ds_write_b128 v188, v[114:117] offset:18432
	ds_write_b128 v188, v[118:121] offset:23040
	ds_write_b128 v188, v[122:125] offset:27648
	ds_write_b128 v188, v[126:129] offset:32256
	v_addc_co_u32_e32 v165, vcc, 0, v161, vcc
	v_add_co_u32_e32 v166, vcc, s84, v160
	s_waitcnt lgkmcnt(0)
	s_nop 0
	v_addc_co_u32_e32 v167, vcc, 0, v161, vcc
	v_add_co_u32_e32 v168, vcc, s81, v158
	s_barrier
	s_nop 0
	v_addc_co_u32_e32 v169, vcc, 0, v159, vcc
	v_add_co_u32_e32 v170, vcc, s80, v158
	s_nop 1
	v_addc_co_u32_e32 v171, vcc, 0, v159, vcc
	v_add_co_u32_e32 v172, vcc, s84, v158
	global_load_dwordx4 v[86:89], v[132:133], off offset:256
	s_nop 0
	v_addc_co_u32_e32 v173, vcc, 0, v159, vcc
	global_load_dwordx4 v[98:101], v[162:163], off offset:256
	global_load_dwordx4 v[102:105], v[164:165], off offset:256
	global_load_dwordx4 v[110:113], v[166:167], off offset:256
	global_load_dwordx4 v[114:117], v[134:135], off offset:256
	global_load_dwordx4 v[118:121], v[168:169], off offset:256
	global_load_dwordx4 v[122:125], v[170:171], off offset:256
	global_load_dwordx4 v[126:129], v[172:173], off offset:256
	s_add_i32 s42, s41, s87
	s_cmpk_gt_u32 s42, 0xff
	s_cselect_b64 s[0:1], -1, 0
	s_cmpk_lt_u32 s42, 0x100
	s_cselect_b64 s[38:39], -1, 0
	s_and_b64 s[44:45], s[38:39], exec
	s_cselect_b32 s43, s42, s41
	s_lshl_b32 s44, s43, 4
	s_and_b32 s43, s43, 7
	s_or_b32 s43, s43, s18
	s_and_b32 s45, s44, 0x380
	s_and_b32 s44, s44, 0xfffffc00
	s_lshl_b32 s43, s43, 7
	s_add_i32 s43, s43, s44
	v_add_u32_e32 v2, s45, v131
	v_add_u32_e32 v4, s43, v131
	v_ashrrev_i32_e32 v3, 31, v2
	v_ashrrev_i32_e32 v5, 31, v4
	v_lshlrev_b64 v[2:3], 11, v[2:3]
	v_lshlrev_b64 v[4:5], 11, v[4:5]
	v_lshl_add_u64 v[132:133], v[136:137], 0, v[2:3]
	v_lshl_add_u64 v[134:135], v[138:139], 0, v[4:5]
	s_setprio 1
	ds_read_b128 v[2:5], v140
	ds_read_b128 v[6:9], v141 offset:18432
	ds_read_b128 v[10:13], v141 offset:23040
	s_waitcnt lgkmcnt(1)
	v_mfma_f32_32x32x16_bf16 v[50:65], v[2:5], v[6:9], 0
	s_waitcnt lgkmcnt(0)
	v_mfma_f32_32x32x16_bf16 v[34:49], v[2:5], v[10:13], 0
	ds_read_b128 v[2:5], v140 offset:4608
	ds_read_b128 v[198:201], v140 offset:32
	ds_read_b128 v[202:205], v141 offset:18464
	ds_read_b128 v[206:209], v141 offset:23072
	s_waitcnt lgkmcnt(1)
	v_mfma_f32_32x32x16_bf16 v[50:65], v[198:201], v[202:205], v[50:65]
	s_waitcnt lgkmcnt(0)
	v_mfma_f32_32x32x16_bf16 v[34:49], v[198:201], v[206:209], v[34:49]
	ds_read_b128 v[198:201], v140 offset:4640
	v_mfma_f32_32x32x16_bf16 v[18:33], v[2:5], v[6:9], 0
	v_mfma_f32_32x32x16_bf16 v[2:17], v[2:5], v[10:13], 0
	s_waitcnt lgkmcnt(0)
	v_mfma_f32_32x32x16_bf16 v[18:33], v[198:201], v[202:205], v[18:33]
	v_mfma_f32_32x32x16_bf16 v[2:17], v[198:201], v[206:209], v[2:17]
	ds_read_b128 v[198:201], v140 offset:64
	ds_read_b128 v[202:205], v141 offset:18496
	ds_read_b128 v[206:209], v141 offset:23104
	s_waitcnt lgkmcnt(1)
	v_mfma_f32_32x32x16_bf16 v[50:65], v[198:201], v[202:205], v[50:65]
	s_waitcnt lgkmcnt(0)
	v_mfma_f32_32x32x16_bf16 v[34:49], v[198:201], v[206:209], v[34:49]
	ds_read_b128 v[198:201], v140 offset:4672
	s_waitcnt lgkmcnt(0)
	v_mfma_f32_32x32x16_bf16 v[18:33], v[198:201], v[202:205], v[18:33]
	v_mfma_f32_32x32x16_bf16 v[2:17], v[198:201], v[206:209], v[2:17]
	ds_read_b128 v[198:201], v140 offset:96
	ds_read_b128 v[202:205], v141 offset:18528
	ds_read_b128 v[206:209], v141 offset:23136
	s_waitcnt lgkmcnt(1)
	v_mfma_f32_32x32x16_bf16 v[50:65], v[198:201], v[202:205], v[50:65]
	s_waitcnt lgkmcnt(0)
	v_mfma_f32_32x32x16_bf16 v[34:49], v[198:201], v[206:209], v[34:49]
	ds_read_b128 v[198:201], v140 offset:4704
	s_waitcnt lgkmcnt(0)
	v_mfma_f32_32x32x16_bf16 v[18:33], v[198:201], v[202:205], v[18:33]
	v_mfma_f32_32x32x16_bf16 v[2:17], v[198:201], v[206:209], v[2:17]
	s_setprio 0
	ds_write_b128 v188, v[66:69] offset:36864
	ds_write_b128 v188, v[70:73] offset:41472
	ds_write_b128 v188, v[74:77] offset:46080
	ds_write_b128 v188, v[78:81] offset:50688
	ds_write_b128 v188, v[82:85] offset:55296
	ds_write_b128 v188, v[90:93] offset:59904
	ds_write_b128 v188, v[94:97] offset:64512
	s_waitcnt vmcnt(8)
	ds_write_b128 v189, v[106:109] offset:13824
	s_waitcnt lgkmcnt(0)
	s_barrier
; __device__ __forceinline__ void gemm_kstep(const u16* sb, int wn, int wt, int r, int h, f32x16 (&acc)[2][2]) {
;   const u16* bw = sb + (wn * 64 + r) * LDT + h * 8;
;   const u16* bx = sb + TILE_U16 + (wt * 64 + r) * LDT + h * 8;
;   __builtin_amdgcn_s_setprio(1);
; #pragma unroll
;   for (int ks = 0; ks < 4; ++ks) {
;     bf16x8 a0 = *(const bf16x8*)(bw + ks * 16);
;     bf16x8 a1 = *(const bf16x8*)(bw + 32 * LDT + ks * 16);
;     bf16x8 b0 = *(const bf16x8*)(bx + ks * 16);
;     bf16x8 b1 = *(const bf16x8*)(bx + 32 * LDT + ks * 16);
;     acc[0][0] = mfma32(a0, b0, acc[0][0]);
;     acc[0][1] = mfma32(a0, b1, acc[0][1]);
;     acc[1][0] = mfma32(a1, b0, acc[1][0]);
;     acc[1][1] = mfma32(a1, b1, acc[1][1]);
;   }
;   __builtin_amdgcn_s_setprio(0);
; }
; __device__ void gemm_phase(const u16* __restrict__ Wb, int ldw, const u16* __restrict__ Xb, int ldx, int K,
;                            u16* __restrict__ outb, int ldo, int ntn, int ntiles, u16* lds) {
;     ...
;     for (int kt = 0; kt < nk; kt += 2) {
;       if (kt + 2 < nk) gs_load(B, gw, ldw, gx, ldx, (kt + 2) * 64);
;       else if (has_next) gs_load(B, gwn, ldw, gxn, ldx, 0);
;       gemm_kstep(lds, wn, wt, r, h, acc);
;       gs_store(A, lds + 2 * TILE_U16, lo);
;       __syncthreads();
;       if (kt + 3 < nk) gs_load(A, gw, ldw, gx, ldx, (kt + 3) * 64);
;       else if (has_next) gs_load(A, gwn, ldw, gxn, ldx, 64);
;       gemm_kstep(lds + 2 * TILE_U16, wn, wt, r, h, acc);
;       if (kt + 2 < nk) gs_store(B, lds, lo);
;       __syncthreads();
;     }
	s_setprio 1
	ds_read_b128 v[198:201], v140 offset:36864
	ds_read_b128 v[202:205], v141 offset:55296
	ds_read_b128 v[206:209], v141 offset:59904
	ds_read_b128 v[214:217], v140 offset:41472
	ds_read_b128 v[218:221], v140 offset:36896
	ds_read_b128 v[222:225], v141 offset:55328
	ds_read_b128 v[226:229], v141 offset:59936
	ds_read_b128 v[230:233], v140 offset:41504
	s_waitcnt lgkmcnt(4)
	v_mfma_f32_32x32x16_bf16 v[50:65], v[198:201], v[202:205], v[50:65]
	v_mfma_f32_32x32x16_bf16 v[34:49], v[198:201], v[206:209], v[34:49]
	v_mfma_f32_32x32x16_bf16 v[18:33], v[214:217], v[202:205], v[18:33]
	v_mfma_f32_32x32x16_bf16 v[2:17], v[214:217], v[206:209], v[2:17]
	global_load_dwordx4 v[66:69], v[160:161], off offset:384
	global_load_dwordx4 v[70:73], v[162:163], off offset:384
	global_load_dwordx4 v[74:77], v[164:165], off offset:384
	global_load_dwordx4 v[78:81], v[166:167], off offset:384
	global_load_dwordx4 v[82:85], v[158:159], off offset:384
	global_load_dwordx4 v[90:93], v[168:169], off offset:384
	global_load_dwordx4 v[94:97], v[170:171], off offset:384
	global_load_dwordx4 v[106:109], v[172:173], off offset:384
	ds_read_b128 v[198:201], v140 offset:36928
	ds_read_b128 v[202:205], v141 offset:55360
	ds_read_b128 v[206:209], v141 offset:59968
	ds_read_b128 v[214:217], v140 offset:41536
	s_waitcnt lgkmcnt(4)
	v_mfma_f32_32x32x16_bf16 v[50:65], v[218:221], v[222:225], v[50:65]
	v_mfma_f32_32x32x16_bf16 v[34:49], v[218:221], v[226:229], v[34:49]
	v_mfma_f32_32x32x16_bf16 v[18:33], v[230:233], v[222:225], v[18:33]
	v_mfma_f32_32x32x16_bf16 v[2:17], v[230:233], v[226:229], v[2:17]
	ds_read_b128 v[218:221], v140 offset:36960
	ds_read_b128 v[222:225], v141 offset:55392
	ds_read_b128 v[226:229], v141 offset:60000
	ds_read_b128 v[230:233], v140 offset:41568
	s_waitcnt lgkmcnt(4)
	v_mfma_f32_32x32x16_bf16 v[50:65], v[198:201], v[202:205], v[50:65]
	v_mfma_f32_32x32x16_bf16 v[34:49], v[198:201], v[206:209], v[34:49]
	v_mfma_f32_32x32x16_bf16 v[18:33], v[214:217], v[202:205], v[18:33]
	v_mfma_f32_32x32x16_bf16 v[2:17], v[214:217], v[206:209], v[2:17]
	s_waitcnt lgkmcnt(0)
	v_mfma_f32_32x32x16_bf16 v[50:65], v[218:221], v[222:225], v[50:65]
	v_mfma_f32_32x32x16_bf16 v[34:49], v[218:221], v[226:229], v[34:49]
	v_mfma_f32_32x32x16_bf16 v[18:33], v[230:233], v[222:225], v[18:33]
	v_mfma_f32_32x32x16_bf16 v[2:17], v[230:233], v[226:229], v[2:17]
	s_setprio 0
	s_waitcnt vmcnt(8)
	ds_write_b128 v188, v[86:89]
	ds_write_b128 v188, v[98:101] offset:4608
	ds_write_b128 v188, v[102:105] offset:9216
	ds_write_b128 v188, v[110:113] offset:13824
	ds_write_b128 v188, v[114:117] offset:18432
	ds_write_b128 v188, v[118:121] offset:23040
	ds_write_b128 v188, v[122:125] offset:27648
	ds_write_b128 v188, v[126:129] offset:32256
	s_waitcnt lgkmcnt(0)
	s_barrier
	s_setprio 1
	ds_read_b128 v[198:201], v140
	ds_read_b128 v[202:205], v141 offset:18432
	ds_read_b128 v[206:209], v141 offset:23040
	ds_read_b128 v[214:217], v140 offset:4608
	ds_read_b128 v[218:221], v140 offset:32
	ds_read_b128 v[222:225], v141 offset:18464
	ds_read_b128 v[226:229], v141 offset:23072
	ds_read_b128 v[230:233], v140 offset:4640
	s_waitcnt lgkmcnt(4)
	v_mfma_f32_32x32x16_bf16 v[50:65], v[198:201], v[202:205], v[50:65]
	v_mfma_f32_32x32x16_bf16 v[34:49], v[198:201], v[206:209], v[34:49]
	v_mfma_f32_32x32x16_bf16 v[18:33], v[214:217], v[202:205], v[18:33]
	v_mfma_f32_32x32x16_bf16 v[2:17], v[214:217], v[206:209], v[2:17]
	global_load_dwordx4 v[86:89], v[160:161], off offset:512
	global_load_dwordx4 v[98:101], v[162:163], off offset:512
	global_load_dwordx4 v[102:105], v[164:165], off offset:512
	global_load_dwordx4 v[110:113], v[166:167], off offset:512
	global_load_dwordx4 v[114:117], v[158:159], off offset:512
	global_load_dwordx4 v[118:121], v[168:169], off offset:512
	global_load_dwordx4 v[122:125], v[170:171], off offset:512
	global_load_dwordx4 v[126:129], v[172:173], off offset:512
	ds_read_b128 v[198:201], v140 offset:64
	ds_read_b128 v[202:205], v141 offset:18496
	ds_read_b128 v[206:209], v141 offset:23104
	ds_read_b128 v[214:217], v140 offset:4672
	s_waitcnt lgkmcnt(4)
	v_mfma_f32_32x32x16_bf16 v[50:65], v[218:221], v[222:225], v[50:65]
	v_mfma_f32_32x32x16_bf16 v[34:49], v[218:221], v[226:229], v[34:49]
	v_mfma_f32_32x32x16_bf16 v[18:33], v[230:233], v[222:225], v[18:33]
	v_mfma_f32_32x32x16_bf16 v[2:17], v[230:233], v[226:229], v[2:17]
	ds_read_b128 v[218:221], v140 offset:96
	ds_read_b128 v[222:225], v141 offset:18528
	ds_read_b128 v[226:229], v141 offset:23136
	ds_read_b128 v[230:233], v140 offset:4704
	s_waitcnt lgkmcnt(4)
	v_mfma_f32_32x32x16_bf16 v[50:65], v[198:201], v[202:205], v[50:65]
	v_mfma_f32_32x32x16_bf16 v[34:49], v[198:201], v[206:209], v[34:49]
	v_mfma_f32_32x32x16_bf16 v[18:33], v[214:217], v[202:205], v[18:33]
	v_mfma_f32_32x32x16_bf16 v[2:17], v[214:217], v[206:209], v[2:17]
	s_waitcnt lgkmcnt(0)
	v_mfma_f32_32x32x16_bf16 v[50:65], v[218:221], v[222:225], v[50:65]
	v_mfma_f32_32x32x16_bf16 v[34:49], v[218:221], v[226:229], v[34:49]
	v_mfma_f32_32x32x16_bf16 v[18:33], v[230:233], v[222:225], v[18:33]
	v_mfma_f32_32x32x16_bf16 v[2:17], v[230:233], v[226:229], v[2:17]
	s_setprio 0
	s_waitcnt vmcnt(8)
	ds_write_b128 v188, v[66:69] offset:36864
	ds_write_b128 v188, v[70:73] offset:41472
	ds_write_b128 v188, v[74:77] offset:46080
	ds_write_b128 v188, v[78:81] offset:50688
	ds_write_b128 v188, v[82:85] offset:55296
	ds_write_b128 v188, v[90:93] offset:59904
	ds_write_b128 v188, v[94:97] offset:64512
	ds_write_b128 v189, v[106:109] offset:13824
	s_waitcnt lgkmcnt(0)
	s_barrier
; __device__ __forceinline__ void gemm_kstep(const u16* sb, int wn, int wt, int r, int h, f32x16 (&acc)[2][2]) {
;   const u16* bw = sb + (wn * 64 + r) * LDT + h * 8;
;   const u16* bx = sb + TILE_U16 + (wt * 64 + r) * LDT + h * 8;
;   __builtin_amdgcn_s_setprio(1);
; #pragma unroll
;   for (int ks = 0; ks < 4; ++ks) {
;     bf16x8 a0 = *(const bf16x8*)(bw + ks * 16);
;     bf16x8 a1 = *(const bf16x8*)(bw + 32 * LDT + ks * 16);
;     bf16x8 b0 = *(const bf16x8*)(bx + ks * 16);
;     bf16x8 b1 = *(const bf16x8*)(bx + 32 * LDT + ks * 16);
;     acc[0][0] = mfma32(a0, b0, acc[0][0]);
;     acc[0][1] = mfma32(a0, b1, acc[0][1]);
;     acc[1][0] = mfma32(a1, b0, acc[1][0]);
;     acc[1][1] = mfma32(a1, b1, acc[1][1]);
;   }
;   __builtin_amdgcn_s_setprio(0);
; }
; __device__ void gemm_phase(const u16* __restrict__ Wb, int ldw, const u16* __restrict__ Xb, int ldx, int K,
;                            u16* __restrict__ outb, int ldo, int ntn, int ntiles, u16* lds) {
;     ...
;     for (int kt = 0; kt < nk; kt += 2) {
;       if (kt + 2 < nk) gs_load(B, gw, ldw, gx, ldx, (kt + 2) * 64);
;       else if (has_next) gs_load(B, gwn, ldw, gxn, ldx, 0);
;       gemm_kstep(lds, wn, wt, r, h, acc);
;       gs_store(A, lds + 2 * TILE_U16, lo);
;       __syncthreads();
;       if (kt + 3 < nk) gs_load(A, gw, ldw, gx, ldx, (kt + 3) * 64);
;       else if (has_next) gs_load(A, gwn, ldw, gxn, ldx, 64);
;       gemm_kstep(lds + 2 * TILE_U16, wn, wt, r, h, acc);
;       if (kt + 2 < nk) gs_store(B, lds, lo);
;       __syncthreads();
;     }
	s_setprio 1
	ds_read_b128 v[198:201], v140 offset:36864
	ds_read_b128 v[202:205], v141 offset:55296
	ds_read_b128 v[206:209], v141 offset:59904
	ds_read_b128 v[214:217], v140 offset:41472
	ds_read_b128 v[218:221], v140 offset:36896
	ds_read_b128 v[222:225], v141 offset:55328
	ds_read_b128 v[226:229], v141 offset:59936
	ds_read_b128 v[230:233], v140 offset:41504
	s_waitcnt lgkmcnt(4)
	v_mfma_f32_32x32x16_bf16 v[50:65], v[198:201], v[202:205], v[50:65]
	v_mfma_f32_32x32x16_bf16 v[34:49], v[198:201], v[206:209], v[34:49]
	v_mfma_f32_32x32x16_bf16 v[18:33], v[214:217], v[202:205], v[18:33]
	v_mfma_f32_32x32x16_bf16 v[2:17], v[214:217], v[206:209], v[2:17]
	global_load_dwordx4 v[66:69], v[160:161], off offset:640
	global_load_dwordx4 v[70:73], v[162:163], off offset:640
	global_load_dwordx4 v[74:77], v[164:165], off offset:640
	global_load_dwordx4 v[78:81], v[166:167], off offset:640
	global_load_dwordx4 v[82:85], v[158:159], off offset:640
	global_load_dwordx4 v[90:93], v[168:169], off offset:640
	global_load_dwordx4 v[94:97], v[170:171], off offset:640
	global_load_dwordx4 v[106:109], v[172:173], off offset:640
	ds_read_b128 v[198:201], v140 offset:36928
	ds_read_b128 v[202:205], v141 offset:55360
	ds_read_b128 v[206:209], v141 offset:59968
	ds_read_b128 v[214:217], v140 offset:41536
	s_waitcnt lgkmcnt(4)
	v_mfma_f32_32x32x16_bf16 v[50:65], v[218:221], v[222:225], v[50:65]
	v_mfma_f32_32x32x16_bf16 v[34:49], v[218:221], v[226:229], v[34:49]
	v_mfma_f32_32x32x16_bf16 v[18:33], v[230:233], v[222:225], v[18:33]
	v_mfma_f32_32x32x16_bf16 v[2:17], v[230:233], v[226:229], v[2:17]
	ds_read_b128 v[218:221], v140 offset:36960
	ds_read_b128 v[222:225], v141 offset:55392
	ds_read_b128 v[226:229], v141 offset:60000
	ds_read_b128 v[230:233], v140 offset:41568
	s_waitcnt lgkmcnt(4)
	v_mfma_f32_32x32x16_bf16 v[50:65], v[198:201], v[202:205], v[50:65]
	v_mfma_f32_32x32x16_bf16 v[34:49], v[198:201], v[206:209], v[34:49]
	v_mfma_f32_32x32x16_bf16 v[18:33], v[214:217], v[202:205], v[18:33]
	v_mfma_f32_32x32x16_bf16 v[2:17], v[214:217], v[206:209], v[2:17]
	s_waitcnt lgkmcnt(0)
	v_mfma_f32_32x32x16_bf16 v[50:65], v[218:221], v[222:225], v[50:65]
	v_mfma_f32_32x32x16_bf16 v[34:49], v[218:221], v[226:229], v[34:49]
	v_mfma_f32_32x32x16_bf16 v[18:33], v[230:233], v[222:225], v[18:33]
	v_mfma_f32_32x32x16_bf16 v[2:17], v[230:233], v[226:229], v[2:17]
	s_setprio 0
	s_waitcnt vmcnt(8)
	ds_write_b128 v188, v[86:89]
	ds_write_b128 v188, v[98:101] offset:4608
	ds_write_b128 v188, v[102:105] offset:9216
	ds_write_b128 v188, v[110:113] offset:13824
	ds_write_b128 v188, v[114:117] offset:18432
	ds_write_b128 v188, v[118:121] offset:23040
	ds_write_b128 v188, v[122:125] offset:27648
	ds_write_b128 v188, v[126:129] offset:32256
	s_waitcnt lgkmcnt(0)
	s_barrier
	s_setprio 1
	ds_read_b128 v[198:201], v140
	ds_read_b128 v[202:205], v141 offset:18432
	ds_read_b128 v[206:209], v141 offset:23040
	ds_read_b128 v[214:217], v140 offset:4608
	ds_read_b128 v[218:221], v140 offset:32
	ds_read_b128 v[222:225], v141 offset:18464
	ds_read_b128 v[226:229], v141 offset:23072
	ds_read_b128 v[230:233], v140 offset:4640
	s_waitcnt lgkmcnt(4)
	v_mfma_f32_32x32x16_bf16 v[50:65], v[198:201], v[202:205], v[50:65]
	v_mfma_f32_32x32x16_bf16 v[34:49], v[198:201], v[206:209], v[34:49]
	v_mfma_f32_32x32x16_bf16 v[18:33], v[214:217], v[202:205], v[18:33]
	v_mfma_f32_32x32x16_bf16 v[2:17], v[214:217], v[206:209], v[2:17]
	global_load_dwordx4 v[86:89], v[160:161], off offset:768
	global_load_dwordx4 v[98:101], v[162:163], off offset:768
	global_load_dwordx4 v[102:105], v[164:165], off offset:768
	global_load_dwordx4 v[110:113], v[166:167], off offset:768
	global_load_dwordx4 v[114:117], v[158:159], off offset:768
	global_load_dwordx4 v[118:121], v[168:169], off offset:768
	global_load_dwordx4 v[122:125], v[170:171], off offset:768
	global_load_dwordx4 v[126:129], v[172:173], off offset:768
	ds_read_b128 v[198:201], v140 offset:64
	ds_read_b128 v[202:205], v141 offset:18496
	ds_read_b128 v[206:209], v141 offset:23104
	ds_read_b128 v[214:217], v140 offset:4672
	s_waitcnt lgkmcnt(4)
	v_mfma_f32_32x32x16_bf16 v[50:65], v[218:221], v[222:225], v[50:65]
	v_mfma_f32_32x32x16_bf16 v[34:49], v[218:221], v[226:229], v[34:49]
	v_mfma_f32_32x32x16_bf16 v[18:33], v[230:233], v[222:225], v[18:33]
	v_mfma_f32_32x32x16_bf16 v[2:17], v[230:233], v[226:229], v[2:17]
	ds_read_b128 v[218:221], v140 offset:96
	ds_read_b128 v[222:225], v141 offset:18528
	ds_read_b128 v[226:229], v141 offset:23136
	ds_read_b128 v[230:233], v140 offset:4704
	s_waitcnt lgkmcnt(4)
	v_mfma_f32_32x32x16_bf16 v[50:65], v[198:201], v[202:205], v[50:65]
	v_mfma_f32_32x32x16_bf16 v[34:49], v[198:201], v[206:209], v[34:49]
	v_mfma_f32_32x32x16_bf16 v[18:33], v[214:217], v[202:205], v[18:33]
	v_mfma_f32_32x32x16_bf16 v[2:17], v[214:217], v[206:209], v[2:17]
	s_waitcnt lgkmcnt(0)
	v_mfma_f32_32x32x16_bf16 v[50:65], v[218:221], v[222:225], v[50:65]
	v_mfma_f32_32x32x16_bf16 v[34:49], v[218:221], v[226:229], v[34:49]
	v_mfma_f32_32x32x16_bf16 v[18:33], v[230:233], v[222:225], v[18:33]
	v_mfma_f32_32x32x16_bf16 v[2:17], v[230:233], v[226:229], v[2:17]
	s_setprio 0
	s_waitcnt vmcnt(8)
	ds_write_b128 v188, v[66:69] offset:36864
	ds_write_b128 v188, v[70:73] offset:41472
	ds_write_b128 v188, v[74:77] offset:46080
	ds_write_b128 v188, v[78:81] offset:50688
	ds_write_b128 v188, v[82:85] offset:55296
	ds_write_b128 v188, v[90:93] offset:59904
	ds_write_b128 v188, v[94:97] offset:64512
	ds_write_b128 v189, v[106:109] offset:13824
	s_waitcnt lgkmcnt(0)
	s_barrier
; __device__ __forceinline__ void gemm_kstep(const u16* sb, int wn, int wt, int r, int h, f32x16 (&acc)[2][2]) {
;   const u16* bw = sb + (wn * 64 + r) * LDT + h * 8;
;   const u16* bx = sb + TILE_U16 + (wt * 64 + r) * LDT + h * 8;
;   __builtin_amdgcn_s_setprio(1);
; #pragma unroll
;   for (int ks = 0; ks < 4; ++ks) {
;     bf16x8 a0 = *(const bf16x8*)(bw + ks * 16);
;     bf16x8 a1 = *(const bf16x8*)(bw + 32 * LDT + ks * 16);
;     bf16x8 b0 = *(const bf16x8*)(bx + ks * 16);
;     bf16x8 b1 = *(const bf16x8*)(bx + 32 * LDT + ks * 16);
;     acc[0][0] = mfma32(a0, b0, acc[0][0]);
;     acc[0][1] = mfma32(a0, b1, acc[0][1]);
;     acc[1][0] = mfma32(a1, b0, acc[1][0]);
;     acc[1][1] = mfma32(a1, b1, acc[1][1]);
;   }
;   __builtin_amdgcn_s_setprio(0);
; }
; __device__ void gemm_phase(const u16* __restrict__ Wb, int ldw, const u16* __restrict__ Xb, int ldx, int K,
;                            u16* __restrict__ outb, int ldo, int ntn, int ntiles, u16* lds) {
;     ...
;     for (int kt = 0; kt < nk; kt += 2) {
;       if (kt + 2 < nk) gs_load(B, gw, ldw, gx, ldx, (kt + 2) * 64);
;       else if (has_next) gs_load(B, gwn, ldw, gxn, ldx, 0);
;       gemm_kstep(lds, wn, wt, r, h, acc);
;       gs_store(A, lds + 2 * TILE_U16, lo);
;       __syncthreads();
;       if (kt + 3 < nk) gs_load(A, gw, ldw, gx, ldx, (kt + 3) * 64);
;       else if (has_next) gs_load(A, gwn, ldw, gxn, ldx, 64);
;       gemm_kstep(lds + 2 * TILE_U16, wn, wt, r, h, acc);
;       if (kt + 2 < nk) gs_store(B, lds, lo);
;       __syncthreads();
;     }
	s_setprio 1
	ds_read_b128 v[198:201], v140 offset:36864
	ds_read_b128 v[202:205], v141 offset:55296
	ds_read_b128 v[206:209], v141 offset:59904
	ds_read_b128 v[214:217], v140 offset:41472
	ds_read_b128 v[218:221], v140 offset:36896
	ds_read_b128 v[222:225], v141 offset:55328
	ds_read_b128 v[226:229], v141 offset:59936
	ds_read_b128 v[230:233], v140 offset:41504
	s_waitcnt lgkmcnt(4)
	v_mfma_f32_32x32x16_bf16 v[50:65], v[198:201], v[202:205], v[50:65]
	v_mfma_f32_32x32x16_bf16 v[34:49], v[198:201], v[206:209], v[34:49]
	v_mfma_f32_32x32x16_bf16 v[18:33], v[214:217], v[202:205], v[18:33]
	v_mfma_f32_32x32x16_bf16 v[2:17], v[214:217], v[206:209], v[2:17]
	global_load_dwordx4 v[66:69], v[160:161], off offset:896
	global_load_dwordx4 v[70:73], v[162:163], off offset:896
	global_load_dwordx4 v[74:77], v[164:165], off offset:896
	global_load_dwordx4 v[78:81], v[166:167], off offset:896
	global_load_dwordx4 v[82:85], v[158:159], off offset:896
	global_load_dwordx4 v[90:93], v[168:169], off offset:896
	global_load_dwordx4 v[94:97], v[170:171], off offset:896
	global_load_dwordx4 v[106:109], v[172:173], off offset:896
	ds_read_b128 v[198:201], v140 offset:36928
	ds_read_b128 v[202:205], v141 offset:55360
	ds_read_b128 v[206:209], v141 offset:59968
	ds_read_b128 v[214:217], v140 offset:41536
	s_waitcnt lgkmcnt(4)
	v_mfma_f32_32x32x16_bf16 v[50:65], v[218:221], v[222:225], v[50:65]
	v_mfma_f32_32x32x16_bf16 v[34:49], v[218:221], v[226:229], v[34:49]
	v_mfma_f32_32x32x16_bf16 v[18:33], v[230:233], v[222:225], v[18:33]
	v_mfma_f32_32x32x16_bf16 v[2:17], v[230:233], v[226:229], v[2:17]
	ds_read_b128 v[218:221], v140 offset:36960
	ds_read_b128 v[222:225], v141 offset:55392
	ds_read_b128 v[226:229], v141 offset:60000
	ds_read_b128 v[230:233], v140 offset:41568
	s_waitcnt lgkmcnt(4)
	v_mfma_f32_32x32x16_bf16 v[50:65], v[198:201], v[202:205], v[50:65]
	v_mfma_f32_32x32x16_bf16 v[34:49], v[198:201], v[206:209], v[34:49]
	v_mfma_f32_32x32x16_bf16 v[18:33], v[214:217], v[202:205], v[18:33]
	v_mfma_f32_32x32x16_bf16 v[2:17], v[214:217], v[206:209], v[2:17]
	s_waitcnt lgkmcnt(0)
	v_mfma_f32_32x32x16_bf16 v[50:65], v[218:221], v[222:225], v[50:65]
	v_mfma_f32_32x32x16_bf16 v[34:49], v[218:221], v[226:229], v[34:49]
	v_mfma_f32_32x32x16_bf16 v[18:33], v[230:233], v[222:225], v[18:33]
	v_mfma_f32_32x32x16_bf16 v[2:17], v[230:233], v[226:229], v[2:17]
	s_setprio 0
	s_waitcnt vmcnt(8)
	ds_write_b128 v188, v[86:89]
	ds_write_b128 v188, v[98:101] offset:4608
	ds_write_b128 v188, v[102:105] offset:9216
	ds_write_b128 v188, v[110:113] offset:13824
	ds_write_b128 v188, v[114:117] offset:18432
	ds_write_b128 v188, v[118:121] offset:23040
	ds_write_b128 v188, v[122:125] offset:27648
	ds_write_b128 v188, v[126:129] offset:32256
	s_waitcnt lgkmcnt(0)
	s_barrier
	s_setprio 1
	ds_read_b128 v[198:201], v140
	ds_read_b128 v[202:205], v141 offset:18432
	ds_read_b128 v[206:209], v141 offset:23040
	ds_read_b128 v[214:217], v140 offset:4608
	ds_read_b128 v[218:221], v140 offset:32
	ds_read_b128 v[222:225], v141 offset:18464
	ds_read_b128 v[226:229], v141 offset:23072
	ds_read_b128 v[230:233], v140 offset:4640
	s_waitcnt lgkmcnt(4)
	v_mfma_f32_32x32x16_bf16 v[50:65], v[198:201], v[202:205], v[50:65]
	v_mfma_f32_32x32x16_bf16 v[34:49], v[198:201], v[206:209], v[34:49]
	v_mfma_f32_32x32x16_bf16 v[18:33], v[214:217], v[202:205], v[18:33]
	v_mfma_f32_32x32x16_bf16 v[2:17], v[214:217], v[206:209], v[2:17]
	global_load_dwordx4 v[86:89], v[160:161], off offset:1024
	global_load_dwordx4 v[98:101], v[162:163], off offset:1024
	global_load_dwordx4 v[102:105], v[164:165], off offset:1024
	global_load_dwordx4 v[110:113], v[166:167], off offset:1024
	global_load_dwordx4 v[114:117], v[158:159], off offset:1024
	global_load_dwordx4 v[118:121], v[168:169], off offset:1024
	global_load_dwordx4 v[122:125], v[170:171], off offset:1024
	global_load_dwordx4 v[126:129], v[172:173], off offset:1024
	ds_read_b128 v[198:201], v140 offset:64
	ds_read_b128 v[202:205], v141 offset:18496
	ds_read_b128 v[206:209], v141 offset:23104
	ds_read_b128 v[214:217], v140 offset:4672
	s_waitcnt lgkmcnt(4)
	v_mfma_f32_32x32x16_bf16 v[50:65], v[218:221], v[222:225], v[50:65]
	v_mfma_f32_32x32x16_bf16 v[34:49], v[218:221], v[226:229], v[34:49]
	v_mfma_f32_32x32x16_bf16 v[18:33], v[230:233], v[222:225], v[18:33]
	v_mfma_f32_32x32x16_bf16 v[2:17], v[230:233], v[226:229], v[2:17]
	ds_read_b128 v[218:221], v140 offset:96
	ds_read_b128 v[222:225], v141 offset:18528
	ds_read_b128 v[226:229], v141 offset:23136
	ds_read_b128 v[230:233], v140 offset:4704
	s_waitcnt lgkmcnt(4)
	v_mfma_f32_32x32x16_bf16 v[50:65], v[198:201], v[202:205], v[50:65]
	v_mfma_f32_32x32x16_bf16 v[34:49], v[198:201], v[206:209], v[34:49]
	v_mfma_f32_32x32x16_bf16 v[18:33], v[214:217], v[202:205], v[18:33]
	v_mfma_f32_32x32x16_bf16 v[2:17], v[214:217], v[206:209], v[2:17]
	s_waitcnt lgkmcnt(0)
	v_mfma_f32_32x32x16_bf16 v[50:65], v[218:221], v[222:225], v[50:65]
	v_mfma_f32_32x32x16_bf16 v[34:49], v[218:221], v[226:229], v[34:49]
	v_mfma_f32_32x32x16_bf16 v[18:33], v[230:233], v[222:225], v[18:33]
	v_mfma_f32_32x32x16_bf16 v[2:17], v[230:233], v[226:229], v[2:17]
	s_setprio 0
	s_waitcnt vmcnt(8)
	ds_write_b128 v188, v[66:69] offset:36864
	ds_write_b128 v188, v[70:73] offset:41472
	ds_write_b128 v188, v[74:77] offset:46080
	ds_write_b128 v188, v[78:81] offset:50688
	ds_write_b128 v188, v[82:85] offset:55296
	ds_write_b128 v188, v[90:93] offset:59904
	ds_write_b128 v188, v[94:97] offset:64512
	ds_write_b128 v189, v[106:109] offset:13824
	s_waitcnt lgkmcnt(0)
	s_barrier
; __device__ __forceinline__ void gemm_kstep(const u16* sb, int wn, int wt, int r, int h, f32x16 (&acc)[2][2]) {
;   const u16* bw = sb + (wn * 64 + r) * LDT + h * 8;
;   const u16* bx = sb + TILE_U16 + (wt * 64 + r) * LDT + h * 8;
;   __builtin_amdgcn_s_setprio(1);
; #pragma unroll
;   for (int ks = 0; ks < 4; ++ks) {
;     bf16x8 a0 = *(const bf16x8*)(bw + ks * 16);
;     bf16x8 a1 = *(const bf16x8*)(bw + 32 * LDT + ks * 16);
;     bf16x8 b0 = *(const bf16x8*)(bx + ks * 16);
;     bf16x8 b1 = *(const bf16x8*)(bx + 32 * LDT + ks * 16);
;     acc[0][0] = mfma32(a0, b0, acc[0][0]);
;     acc[0][1] = mfma32(a0, b1, acc[0][1]);
;     acc[1][0] = mfma32(a1, b0, acc[1][0]);
;     acc[1][1] = mfma32(a1, b1, acc[1][1]);
;   }
;   __builtin_amdgcn_s_setprio(0);
; }
; __device__ void gemm_phase(const u16* __restrict__ Wb, int ldw, const u16* __restrict__ Xb, int ldx, int K,
;                            u16* __restrict__ outb, int ldo, int ntn, int ntiles, u16* lds) {
;     ...
;     for (int kt = 0; kt < nk; kt += 2) {
;       if (kt + 2 < nk) gs_load(B, gw, ldw, gx, ldx, (kt + 2) * 64);
;       else if (has_next) gs_load(B, gwn, ldw, gxn, ldx, 0);
;       gemm_kstep(lds, wn, wt, r, h, acc);
;       gs_store(A, lds + 2 * TILE_U16, lo);
;       __syncthreads();
;       if (kt + 3 < nk) gs_load(A, gw, ldw, gx, ldx, (kt + 3) * 64);
;       else if (has_next) gs_load(A, gwn, ldw, gxn, ldx, 64);
;       gemm_kstep(lds + 2 * TILE_U16, wn, wt, r, h, acc);
;       if (kt + 2 < nk) gs_store(B, lds, lo);
;       __syncthreads();
;     }
	s_setprio 1
	ds_read_b128 v[198:201], v140 offset:36864
	ds_read_b128 v[202:205], v141 offset:55296
	ds_read_b128 v[206:209], v141 offset:59904
	ds_read_b128 v[214:217], v140 offset:41472
	ds_read_b128 v[218:221], v140 offset:36896
	ds_read_b128 v[222:225], v141 offset:55328
	ds_read_b128 v[226:229], v141 offset:59936
	ds_read_b128 v[230:233], v140 offset:41504
	s_waitcnt lgkmcnt(4)
	v_mfma_f32_32x32x16_bf16 v[50:65], v[198:201], v[202:205], v[50:65]
	v_mfma_f32_32x32x16_bf16 v[34:49], v[198:201], v[206:209], v[34:49]
	v_mfma_f32_32x32x16_bf16 v[18:33], v[214:217], v[202:205], v[18:33]
	v_mfma_f32_32x32x16_bf16 v[2:17], v[214:217], v[206:209], v[2:17]
	global_load_dwordx4 v[66:69], v[160:161], off offset:1152
	global_load_dwordx4 v[70:73], v[162:163], off offset:1152
	global_load_dwordx4 v[74:77], v[164:165], off offset:1152
	global_load_dwordx4 v[78:81], v[166:167], off offset:1152
	global_load_dwordx4 v[82:85], v[158:159], off offset:1152
	global_load_dwordx4 v[90:93], v[168:169], off offset:1152
	global_load_dwordx4 v[94:97], v[170:171], off offset:1152
	global_load_dwordx4 v[106:109], v[172:173], off offset:1152
	ds_read_b128 v[198:201], v140 offset:36928
	ds_read_b128 v[202:205], v141 offset:55360
	ds_read_b128 v[206:209], v141 offset:59968
	ds_read_b128 v[214:217], v140 offset:41536
	s_waitcnt lgkmcnt(4)
	v_mfma_f32_32x32x16_bf16 v[50:65], v[218:221], v[222:225], v[50:65]
	v_mfma_f32_32x32x16_bf16 v[34:49], v[218:221], v[226:229], v[34:49]
	v_mfma_f32_32x32x16_bf16 v[18:33], v[230:233], v[222:225], v[18:33]
	v_mfma_f32_32x32x16_bf16 v[2:17], v[230:233], v[226:229], v[2:17]
	ds_read_b128 v[218:221], v140 offset:36960
	ds_read_b128 v[222:225], v141 offset:55392
	ds_read_b128 v[226:229], v141 offset:60000
	ds_read_b128 v[230:233], v140 offset:41568
	s_waitcnt lgkmcnt(4)
	v_mfma_f32_32x32x16_bf16 v[50:65], v[198:201], v[202:205], v[50:65]
	v_mfma_f32_32x32x16_bf16 v[34:49], v[198:201], v[206:209], v[34:49]
	v_mfma_f32_32x32x16_bf16 v[18:33], v[214:217], v[202:205], v[18:33]
	v_mfma_f32_32x32x16_bf16 v[2:17], v[214:217], v[206:209], v[2:17]
	s_waitcnt lgkmcnt(0)
	v_mfma_f32_32x32x16_bf16 v[50:65], v[218:221], v[222:225], v[50:65]
	v_mfma_f32_32x32x16_bf16 v[34:49], v[218:221], v[226:229], v[34:49]
	v_mfma_f32_32x32x16_bf16 v[18:33], v[230:233], v[222:225], v[18:33]
	v_mfma_f32_32x32x16_bf16 v[2:17], v[230:233], v[226:229], v[2:17]
	s_setprio 0
	s_waitcnt vmcnt(8)
	ds_write_b128 v188, v[86:89]
	ds_write_b128 v188, v[98:101] offset:4608
	ds_write_b128 v188, v[102:105] offset:9216
	ds_write_b128 v188, v[110:113] offset:13824
	ds_write_b128 v188, v[114:117] offset:18432
	ds_write_b128 v188, v[118:121] offset:23040
	ds_write_b128 v188, v[122:125] offset:27648
	ds_write_b128 v188, v[126:129] offset:32256
	s_waitcnt lgkmcnt(0)
	s_barrier
	s_setprio 1
	ds_read_b128 v[198:201], v140
	ds_read_b128 v[202:205], v141 offset:18432
	ds_read_b128 v[206:209], v141 offset:23040
	ds_read_b128 v[214:217], v140 offset:4608
	ds_read_b128 v[218:221], v140 offset:32
	ds_read_b128 v[222:225], v141 offset:18464
	ds_read_b128 v[226:229], v141 offset:23072
	ds_read_b128 v[230:233], v140 offset:4640
	s_waitcnt lgkmcnt(4)
	v_mfma_f32_32x32x16_bf16 v[50:65], v[198:201], v[202:205], v[50:65]
	v_mfma_f32_32x32x16_bf16 v[34:49], v[198:201], v[206:209], v[34:49]
	v_mfma_f32_32x32x16_bf16 v[18:33], v[214:217], v[202:205], v[18:33]
	v_mfma_f32_32x32x16_bf16 v[2:17], v[214:217], v[206:209], v[2:17]
	global_load_dwordx4 v[86:89], v[160:161], off offset:1280
	global_load_dwordx4 v[98:101], v[162:163], off offset:1280
	global_load_dwordx4 v[102:105], v[164:165], off offset:1280
	global_load_dwordx4 v[110:113], v[166:167], off offset:1280
	global_load_dwordx4 v[114:117], v[158:159], off offset:1280
	global_load_dwordx4 v[118:121], v[168:169], off offset:1280
	global_load_dwordx4 v[122:125], v[170:171], off offset:1280
	global_load_dwordx4 v[126:129], v[172:173], off offset:1280
	ds_read_b128 v[198:201], v140 offset:64
	ds_read_b128 v[202:205], v141 offset:18496
	ds_read_b128 v[206:209], v141 offset:23104
	ds_read_b128 v[214:217], v140 offset:4672
	s_waitcnt lgkmcnt(4)
	v_mfma_f32_32x32x16_bf16 v[50:65], v[218:221], v[222:225], v[50:65]
	v_mfma_f32_32x32x16_bf16 v[34:49], v[218:221], v[226:229], v[34:49]
	v_mfma_f32_32x32x16_bf16 v[18:33], v[230:233], v[222:225], v[18:33]
	v_mfma_f32_32x32x16_bf16 v[2:17], v[230:233], v[226:229], v[2:17]
	ds_read_b128 v[218:221], v140 offset:96
	ds_read_b128 v[222:225], v141 offset:18528
	ds_read_b128 v[226:229], v141 offset:23136
	ds_read_b128 v[230:233], v140 offset:4704
	s_waitcnt lgkmcnt(4)
	v_mfma_f32_32x32x16_bf16 v[50:65], v[198:201], v[202:205], v[50:65]
	v_mfma_f32_32x32x16_bf16 v[34:49], v[198:201], v[206:209], v[34:49]
	v_mfma_f32_32x32x16_bf16 v[18:33], v[214:217], v[202:205], v[18:33]
	v_mfma_f32_32x32x16_bf16 v[2:17], v[214:217], v[206:209], v[2:17]
	s_waitcnt lgkmcnt(0)
	v_mfma_f32_32x32x16_bf16 v[50:65], v[218:221], v[222:225], v[50:65]
	v_mfma_f32_32x32x16_bf16 v[34:49], v[218:221], v[226:229], v[34:49]
	v_mfma_f32_32x32x16_bf16 v[18:33], v[230:233], v[222:225], v[18:33]
	v_mfma_f32_32x32x16_bf16 v[2:17], v[230:233], v[226:229], v[2:17]
	s_setprio 0
	s_waitcnt vmcnt(8)
	ds_write_b128 v188, v[66:69] offset:36864
	ds_write_b128 v188, v[70:73] offset:41472
	ds_write_b128 v188, v[74:77] offset:46080
	ds_write_b128 v188, v[78:81] offset:50688
	ds_write_b128 v188, v[82:85] offset:55296
	ds_write_b128 v188, v[90:93] offset:59904
	ds_write_b128 v188, v[94:97] offset:64512
	ds_write_b128 v189, v[106:109] offset:13824
	s_waitcnt lgkmcnt(0)
	s_barrier
; __device__ __forceinline__ void gemm_kstep(const u16* sb, int wn, int wt, int r, int h, f32x16 (&acc)[2][2]) {
;   const u16* bw = sb + (wn * 64 + r) * LDT + h * 8;
;   const u16* bx = sb + TILE_U16 + (wt * 64 + r) * LDT + h * 8;
;   __builtin_amdgcn_s_setprio(1);
; #pragma unroll
;   for (int ks = 0; ks < 4; ++ks) {
;     bf16x8 a0 = *(const bf16x8*)(bw + ks * 16);
;     bf16x8 a1 = *(const bf16x8*)(bw + 32 * LDT + ks * 16);
;     bf16x8 b0 = *(const bf16x8*)(bx + ks * 16);
;     bf16x8 b1 = *(const bf16x8*)(bx + 32 * LDT + ks * 16);
;     acc[0][0] = mfma32(a0, b0, acc[0][0]);
;     acc[0][1] = mfma32(a0, b1, acc[0][1]);
;     acc[1][0] = mfma32(a1, b0, acc[1][0]);
;     acc[1][1] = mfma32(a1, b1, acc[1][1]);
;   }
;   __builtin_amdgcn_s_setprio(0);
; }
; __device__ void gemm_phase(const u16* __restrict__ Wb, int ldw, const u16* __restrict__ Xb, int ldx, int K,
;                            u16* __restrict__ outb, int ldo, int ntn, int ntiles, u16* lds) {
;     ...
;     for (int kt = 0; kt < nk; kt += 2) {
;       if (kt + 2 < nk) gs_load(B, gw, ldw, gx, ldx, (kt + 2) * 64);
;       else if (has_next) gs_load(B, gwn, ldw, gxn, ldx, 0);
;       gemm_kstep(lds, wn, wt, r, h, acc);
;       gs_store(A, lds + 2 * TILE_U16, lo);
;       __syncthreads();
;       if (kt + 3 < nk) gs_load(A, gw, ldw, gx, ldx, (kt + 3) * 64);
;       else if (has_next) gs_load(A, gwn, ldw, gxn, ldx, 64);
;       gemm_kstep(lds + 2 * TILE_U16, wn, wt, r, h, acc);
;       if (kt + 2 < nk) gs_store(B, lds, lo);
;       __syncthreads();
;     }
	s_setprio 1
	ds_read_b128 v[198:201], v140 offset:36864
	ds_read_b128 v[202:205], v141 offset:55296
	ds_read_b128 v[206:209], v141 offset:59904
	ds_read_b128 v[214:217], v140 offset:41472
	ds_read_b128 v[218:221], v140 offset:36896
	ds_read_b128 v[222:225], v141 offset:55328
	ds_read_b128 v[226:229], v141 offset:59936
	ds_read_b128 v[230:233], v140 offset:41504
	s_waitcnt lgkmcnt(4)
	v_mfma_f32_32x32x16_bf16 v[50:65], v[198:201], v[202:205], v[50:65]
	v_mfma_f32_32x32x16_bf16 v[34:49], v[198:201], v[206:209], v[34:49]
	v_mfma_f32_32x32x16_bf16 v[18:33], v[214:217], v[202:205], v[18:33]
	v_mfma_f32_32x32x16_bf16 v[2:17], v[214:217], v[206:209], v[2:17]
	global_load_dwordx4 v[66:69], v[160:161], off offset:1408
	global_load_dwordx4 v[70:73], v[162:163], off offset:1408
	global_load_dwordx4 v[74:77], v[164:165], off offset:1408
	global_load_dwordx4 v[78:81], v[166:167], off offset:1408
	global_load_dwordx4 v[82:85], v[158:159], off offset:1408
	global_load_dwordx4 v[90:93], v[168:169], off offset:1408
	global_load_dwordx4 v[94:97], v[170:171], off offset:1408
	global_load_dwordx4 v[106:109], v[172:173], off offset:1408
	ds_read_b128 v[198:201], v140 offset:36928
	ds_read_b128 v[202:205], v141 offset:55360
	ds_read_b128 v[206:209], v141 offset:59968
	ds_read_b128 v[214:217], v140 offset:41536
	s_waitcnt lgkmcnt(4)
	v_mfma_f32_32x32x16_bf16 v[50:65], v[218:221], v[222:225], v[50:65]
	v_mfma_f32_32x32x16_bf16 v[34:49], v[218:221], v[226:229], v[34:49]
	v_mfma_f32_32x32x16_bf16 v[18:33], v[230:233], v[222:225], v[18:33]
	v_mfma_f32_32x32x16_bf16 v[2:17], v[230:233], v[226:229], v[2:17]
	ds_read_b128 v[218:221], v140 offset:36960
	ds_read_b128 v[222:225], v141 offset:55392
	ds_read_b128 v[226:229], v141 offset:60000
	ds_read_b128 v[230:233], v140 offset:41568
	s_waitcnt lgkmcnt(4)
	v_mfma_f32_32x32x16_bf16 v[50:65], v[198:201], v[202:205], v[50:65]
	v_mfma_f32_32x32x16_bf16 v[34:49], v[198:201], v[206:209], v[34:49]
	v_mfma_f32_32x32x16_bf16 v[18:33], v[214:217], v[202:205], v[18:33]
	v_mfma_f32_32x32x16_bf16 v[2:17], v[214:217], v[206:209], v[2:17]
	s_waitcnt lgkmcnt(0)
	v_mfma_f32_32x32x16_bf16 v[50:65], v[218:221], v[222:225], v[50:65]
	v_mfma_f32_32x32x16_bf16 v[34:49], v[218:221], v[226:229], v[34:49]
	v_mfma_f32_32x32x16_bf16 v[18:33], v[230:233], v[222:225], v[18:33]
	v_mfma_f32_32x32x16_bf16 v[2:17], v[230:233], v[226:229], v[2:17]
	s_setprio 0
	s_waitcnt vmcnt(8)
	ds_write_b128 v188, v[86:89]
	ds_write_b128 v188, v[98:101] offset:4608
	ds_write_b128 v188, v[102:105] offset:9216
	ds_write_b128 v188, v[110:113] offset:13824
	ds_write_b128 v188, v[114:117] offset:18432
	ds_write_b128 v188, v[118:121] offset:23040
	ds_write_b128 v188, v[122:125] offset:27648
	ds_write_b128 v188, v[126:129] offset:32256
	s_waitcnt lgkmcnt(0)
	s_barrier
	s_setprio 1
	ds_read_b128 v[198:201], v140
	ds_read_b128 v[202:205], v141 offset:18432
	ds_read_b128 v[206:209], v141 offset:23040
	ds_read_b128 v[214:217], v140 offset:4608
	ds_read_b128 v[218:221], v140 offset:32
	ds_read_b128 v[222:225], v141 offset:18464
	ds_read_b128 v[226:229], v141 offset:23072
	ds_read_b128 v[230:233], v140 offset:4640
	s_waitcnt lgkmcnt(4)
	v_mfma_f32_32x32x16_bf16 v[50:65], v[198:201], v[202:205], v[50:65]
	v_mfma_f32_32x32x16_bf16 v[34:49], v[198:201], v[206:209], v[34:49]
	v_mfma_f32_32x32x16_bf16 v[18:33], v[214:217], v[202:205], v[18:33]
	v_mfma_f32_32x32x16_bf16 v[2:17], v[214:217], v[206:209], v[2:17]
	global_load_dwordx4 v[86:89], v[160:161], off offset:1536
	global_load_dwordx4 v[98:101], v[162:163], off offset:1536
	global_load_dwordx4 v[102:105], v[164:165], off offset:1536
	global_load_dwordx4 v[110:113], v[166:167], off offset:1536
	global_load_dwordx4 v[114:117], v[158:159], off offset:1536
	global_load_dwordx4 v[118:121], v[168:169], off offset:1536
	global_load_dwordx4 v[122:125], v[170:171], off offset:1536
	global_load_dwordx4 v[126:129], v[172:173], off offset:1536
	ds_read_b128 v[198:201], v140 offset:64
	ds_read_b128 v[202:205], v141 offset:18496
	ds_read_b128 v[206:209], v141 offset:23104
	ds_read_b128 v[214:217], v140 offset:4672
	s_waitcnt lgkmcnt(4)
	v_mfma_f32_32x32x16_bf16 v[50:65], v[218:221], v[222:225], v[50:65]
	v_mfma_f32_32x32x16_bf16 v[34:49], v[218:221], v[226:229], v[34:49]
	v_mfma_f32_32x32x16_bf16 v[18:33], v[230:233], v[222:225], v[18:33]
	v_mfma_f32_32x32x16_bf16 v[2:17], v[230:233], v[226:229], v[2:17]
	ds_read_b128 v[218:221], v140 offset:96
	ds_read_b128 v[222:225], v141 offset:18528
	ds_read_b128 v[226:229], v141 offset:23136
	ds_read_b128 v[230:233], v140 offset:4704
	s_waitcnt lgkmcnt(4)
	v_mfma_f32_32x32x16_bf16 v[50:65], v[198:201], v[202:205], v[50:65]
	v_mfma_f32_32x32x16_bf16 v[34:49], v[198:201], v[206:209], v[34:49]
	v_mfma_f32_32x32x16_bf16 v[18:33], v[214:217], v[202:205], v[18:33]
	v_mfma_f32_32x32x16_bf16 v[2:17], v[214:217], v[206:209], v[2:17]
	s_waitcnt lgkmcnt(0)
	v_mfma_f32_32x32x16_bf16 v[50:65], v[218:221], v[222:225], v[50:65]
	v_mfma_f32_32x32x16_bf16 v[34:49], v[218:221], v[226:229], v[34:49]
	v_mfma_f32_32x32x16_bf16 v[18:33], v[230:233], v[222:225], v[18:33]
	v_mfma_f32_32x32x16_bf16 v[2:17], v[230:233], v[226:229], v[2:17]
	s_setprio 0
	s_waitcnt vmcnt(8)
	ds_write_b128 v188, v[66:69] offset:36864
	ds_write_b128 v188, v[70:73] offset:41472
	ds_write_b128 v188, v[74:77] offset:46080
	ds_write_b128 v188, v[78:81] offset:50688
	ds_write_b128 v188, v[82:85] offset:55296
	ds_write_b128 v188, v[90:93] offset:59904
	ds_write_b128 v188, v[94:97] offset:64512
	ds_write_b128 v189, v[106:109] offset:13824
	s_waitcnt lgkmcnt(0)
	s_barrier
; __device__ __forceinline__ void gemm_kstep(const u16* sb, int wn, int wt, int r, int h, f32x16 (&acc)[2][2]) {
;   const u16* bw = sb + (wn * 64 + r) * LDT + h * 8;
;   const u16* bx = sb + TILE_U16 + (wt * 64 + r) * LDT + h * 8;
;   __builtin_amdgcn_s_setprio(1);
; #pragma unroll
;   for (int ks = 0; ks < 4; ++ks) {
;     bf16x8 a0 = *(const bf16x8*)(bw + ks * 16);
;     bf16x8 a1 = *(const bf16x8*)(bw + 32 * LDT + ks * 16);
;     bf16x8 b0 = *(const bf16x8*)(bx + ks * 16);
;     bf16x8 b1 = *(const bf16x8*)(bx + 32 * LDT + ks * 16);
;     acc[0][0] = mfma32(a0, b0, acc[0][0]);
;     acc[0][1] = mfma32(a0, b1, acc[0][1]);
;     acc[1][0] = mfma32(a1, b0, acc[1][0]);
;     acc[1][1] = mfma32(a1, b1, acc[1][1]);
;   }
;   __builtin_amdgcn_s_setprio(0);
; }
; __device__ void gemm_phase(const u16* __restrict__ Wb, int ldw, const u16* __restrict__ Xb, int ldx, int K,
;                            u16* __restrict__ outb, int ldo, int ntn, int ntiles, u16* lds) {
;     ...
;     for (int kt = 0; kt < nk; kt += 2) {
;       if (kt + 2 < nk) gs_load(B, gw, ldw, gx, ldx, (kt + 2) * 64);
;       else if (has_next) gs_load(B, gwn, ldw, gxn, ldx, 0);
;       gemm_kstep(lds, wn, wt, r, h, acc);
;       gs_store(A, lds + 2 * TILE_U16, lo);
;       __syncthreads();
;       if (kt + 3 < nk) gs_load(A, gw, ldw, gx, ldx, (kt + 3) * 64);
;       else if (has_next) gs_load(A, gwn, ldw, gxn, ldx, 64);
;       gemm_kstep(lds + 2 * TILE_U16, wn, wt, r, h, acc);
;       if (kt + 2 < nk) gs_store(B, lds, lo);
;       __syncthreads();
;     }
	s_setprio 1
	ds_read_b128 v[198:201], v140 offset:36864
	ds_read_b128 v[202:205], v141 offset:55296
	ds_read_b128 v[206:209], v141 offset:59904
	ds_read_b128 v[214:217], v140 offset:41472
	ds_read_b128 v[218:221], v140 offset:36896
	ds_read_b128 v[222:225], v141 offset:55328
	ds_read_b128 v[226:229], v141 offset:59936
	ds_read_b128 v[230:233], v140 offset:41504
	s_waitcnt lgkmcnt(4)
	v_mfma_f32_32x32x16_bf16 v[50:65], v[198:201], v[202:205], v[50:65]
	v_mfma_f32_32x32x16_bf16 v[34:49], v[198:201], v[206:209], v[34:49]
	v_mfma_f32_32x32x16_bf16 v[18:33], v[214:217], v[202:205], v[18:33]
	v_mfma_f32_32x32x16_bf16 v[2:17], v[214:217], v[206:209], v[2:17]
	global_load_dwordx4 v[66:69], v[160:161], off offset:1664
	global_load_dwordx4 v[70:73], v[162:163], off offset:1664
	global_load_dwordx4 v[74:77], v[164:165], off offset:1664
	global_load_dwordx4 v[78:81], v[166:167], off offset:1664
	global_load_dwordx4 v[82:85], v[158:159], off offset:1664
	global_load_dwordx4 v[90:93], v[168:169], off offset:1664
	global_load_dwordx4 v[94:97], v[170:171], off offset:1664
	global_load_dwordx4 v[106:109], v[172:173], off offset:1664
	ds_read_b128 v[198:201], v140 offset:36928
	ds_read_b128 v[202:205], v141 offset:55360
	ds_read_b128 v[206:209], v141 offset:59968
	ds_read_b128 v[214:217], v140 offset:41536
	s_waitcnt lgkmcnt(4)
	v_mfma_f32_32x32x16_bf16 v[50:65], v[218:221], v[222:225], v[50:65]
	v_mfma_f32_32x32x16_bf16 v[34:49], v[218:221], v[226:229], v[34:49]
	v_mfma_f32_32x32x16_bf16 v[18:33], v[230:233], v[222:225], v[18:33]
	v_mfma_f32_32x32x16_bf16 v[2:17], v[230:233], v[226:229], v[2:17]
	ds_read_b128 v[218:221], v140 offset:36960
	ds_read_b128 v[222:225], v141 offset:55392
	ds_read_b128 v[226:229], v141 offset:60000
	ds_read_b128 v[230:233], v140 offset:41568
	s_waitcnt lgkmcnt(4)
	v_mfma_f32_32x32x16_bf16 v[50:65], v[198:201], v[202:205], v[50:65]
	v_mfma_f32_32x32x16_bf16 v[34:49], v[198:201], v[206:209], v[34:49]
	v_mfma_f32_32x32x16_bf16 v[18:33], v[214:217], v[202:205], v[18:33]
	v_mfma_f32_32x32x16_bf16 v[2:17], v[214:217], v[206:209], v[2:17]
	s_waitcnt lgkmcnt(0)
	v_mfma_f32_32x32x16_bf16 v[50:65], v[218:221], v[222:225], v[50:65]
	v_mfma_f32_32x32x16_bf16 v[34:49], v[218:221], v[226:229], v[34:49]
	v_mfma_f32_32x32x16_bf16 v[18:33], v[230:233], v[222:225], v[18:33]
	v_mfma_f32_32x32x16_bf16 v[2:17], v[230:233], v[226:229], v[2:17]
	s_setprio 0
	s_waitcnt vmcnt(8)
	ds_write_b128 v188, v[86:89]
	ds_write_b128 v188, v[98:101] offset:4608
	ds_write_b128 v188, v[102:105] offset:9216
	ds_write_b128 v188, v[110:113] offset:13824
	ds_write_b128 v188, v[114:117] offset:18432
	ds_write_b128 v188, v[118:121] offset:23040
	ds_write_b128 v188, v[122:125] offset:27648
	ds_write_b128 v188, v[126:129] offset:32256
	s_waitcnt lgkmcnt(0)
	s_barrier
	s_setprio 1
	ds_read_b128 v[198:201], v140
	ds_read_b128 v[202:205], v141 offset:18432
	ds_read_b128 v[206:209], v141 offset:23040
	ds_read_b128 v[214:217], v140 offset:4608
	ds_read_b128 v[218:221], v140 offset:32
	ds_read_b128 v[222:225], v141 offset:18464
	ds_read_b128 v[226:229], v141 offset:23072
	ds_read_b128 v[230:233], v140 offset:4640
	s_waitcnt lgkmcnt(4)
	v_mfma_f32_32x32x16_bf16 v[50:65], v[198:201], v[202:205], v[50:65]
	v_mfma_f32_32x32x16_bf16 v[34:49], v[198:201], v[206:209], v[34:49]
	v_mfma_f32_32x32x16_bf16 v[18:33], v[214:217], v[202:205], v[18:33]
	v_mfma_f32_32x32x16_bf16 v[2:17], v[214:217], v[206:209], v[2:17]
	global_load_dwordx4 v[86:89], v[160:161], off offset:1792
	global_load_dwordx4 v[98:101], v[162:163], off offset:1792
	global_load_dwordx4 v[102:105], v[164:165], off offset:1792
	global_load_dwordx4 v[110:113], v[166:167], off offset:1792
	global_load_dwordx4 v[114:117], v[158:159], off offset:1792
	global_load_dwordx4 v[118:121], v[168:169], off offset:1792
	global_load_dwordx4 v[122:125], v[170:171], off offset:1792
	global_load_dwordx4 v[126:129], v[172:173], off offset:1792
	ds_read_b128 v[198:201], v140 offset:64
	ds_read_b128 v[202:205], v141 offset:18496
	ds_read_b128 v[206:209], v141 offset:23104
	ds_read_b128 v[214:217], v140 offset:4672
	s_waitcnt lgkmcnt(4)
	v_mfma_f32_32x32x16_bf16 v[50:65], v[218:221], v[222:225], v[50:65]
	v_mfma_f32_32x32x16_bf16 v[34:49], v[218:221], v[226:229], v[34:49]
	v_mfma_f32_32x32x16_bf16 v[18:33], v[230:233], v[222:225], v[18:33]
	v_mfma_f32_32x32x16_bf16 v[2:17], v[230:233], v[226:229], v[2:17]
	ds_read_b128 v[218:221], v140 offset:96
	ds_read_b128 v[222:225], v141 offset:18528
	ds_read_b128 v[226:229], v141 offset:23136
	ds_read_b128 v[230:233], v140 offset:4704
	s_waitcnt lgkmcnt(4)
	v_mfma_f32_32x32x16_bf16 v[50:65], v[198:201], v[202:205], v[50:65]
	v_mfma_f32_32x32x16_bf16 v[34:49], v[198:201], v[206:209], v[34:49]
	v_mfma_f32_32x32x16_bf16 v[18:33], v[214:217], v[202:205], v[18:33]
	v_mfma_f32_32x32x16_bf16 v[2:17], v[214:217], v[206:209], v[2:17]
	s_waitcnt lgkmcnt(0)
	v_mfma_f32_32x32x16_bf16 v[50:65], v[218:221], v[222:225], v[50:65]
	v_mfma_f32_32x32x16_bf16 v[34:49], v[218:221], v[226:229], v[34:49]
	v_mfma_f32_32x32x16_bf16 v[18:33], v[230:233], v[222:225], v[18:33]
	v_mfma_f32_32x32x16_bf16 v[2:17], v[230:233], v[226:229], v[2:17]
	s_setprio 0
	s_waitcnt vmcnt(8)
	ds_write_b128 v188, v[66:69] offset:36864
	ds_write_b128 v188, v[70:73] offset:41472
	ds_write_b128 v188, v[74:77] offset:46080
	ds_write_b128 v188, v[78:81] offset:50688
	ds_write_b128 v188, v[82:85] offset:55296
	ds_write_b128 v188, v[90:93] offset:59904
	ds_write_b128 v188, v[94:97] offset:64512
	ds_write_b128 v189, v[106:109] offset:13824
	s_waitcnt lgkmcnt(0)
	s_barrier
; __device__ __forceinline__ void gemm_kstep(const u16* sb, int wn, int wt, int r, int h, f32x16 (&acc)[2][2]) {
;   const u16* bw = sb + (wn * 64 + r) * LDT + h * 8;
;   const u16* bx = sb + TILE_U16 + (wt * 64 + r) * LDT + h * 8;
;   __builtin_amdgcn_s_setprio(1);
; #pragma unroll
;   for (int ks = 0; ks < 4; ++ks) {
;     bf16x8 a0 = *(const bf16x8*)(bw + ks * 16);
;     bf16x8 a1 = *(const bf16x8*)(bw + 32 * LDT + ks * 16);
;     bf16x8 b0 = *(const bf16x8*)(bx + ks * 16);
;     bf16x8 b1 = *(const bf16x8*)(bx + 32 * LDT + ks * 16);
;     acc[0][0] = mfma32(a0, b0, acc[0][0]);
;     acc[0][1] = mfma32(a0, b1, acc[0][1]);
;     acc[1][0] = mfma32(a1, b0, acc[1][0]);
;     acc[1][1] = mfma32(a1, b1, acc[1][1]);
;   }
;   __builtin_amdgcn_s_setprio(0);
; }
; __device__ void gemm_phase(const u16* __restrict__ Wb, int ldw, const u16* __restrict__ Xb, int ldx, int K,
;                            u16* __restrict__ outb, int ldo, int ntn, int ntiles, u16* lds) {
;     ...
;     for (int kt = 0; kt < nk; kt += 2) {
;       if (kt + 2 < nk) gs_load(B, gw, ldw, gx, ldx, (kt + 2) * 64);
;       else if (has_next) gs_load(B, gwn, ldw, gxn, ldx, 0);
;       gemm_kstep(lds, wn, wt, r, h, acc);
;       gs_store(A, lds + 2 * TILE_U16, lo);
;       __syncthreads();
;       if (kt + 3 < nk) gs_load(A, gw, ldw, gx, ldx, (kt + 3) * 64);
;       else if (has_next) gs_load(A, gwn, ldw, gxn, ldx, 64);
;       gemm_kstep(lds + 2 * TILE_U16, wn, wt, r, h, acc);
;       if (kt + 2 < nk) gs_store(B, lds, lo);
;       __syncthreads();
;     }
	global_load_dwordx4 v[66:69], v[160:161], off offset:1920
	global_load_dwordx4 v[70:73], v[162:163], off offset:1920
	global_load_dwordx4 v[74:77], v[164:165], off offset:1920
	global_load_dwordx4 v[78:81], v[166:167], off offset:1920
	global_load_dwordx4 v[82:85], v[158:159], off offset:1920
	global_load_dwordx4 v[90:93], v[168:169], off offset:1920
	global_load_dwordx4 v[94:97], v[170:171], off offset:1920
	global_load_dwordx4 v[106:109], v[172:173], off offset:1920
	s_setprio 1
	ds_read_b128 v[158:161], v140 offset:36864
	ds_read_b128 v[162:165], v141 offset:55296
	ds_read_b128 v[166:169], v141 offset:59904
	ds_read_b128 v[214:217], v140 offset:41472
	ds_read_b128 v[218:221], v140 offset:36896
	ds_read_b128 v[222:225], v141 offset:55328
	ds_read_b128 v[226:229], v141 offset:59936
	ds_read_b128 v[230:233], v140 offset:41504
	s_waitcnt lgkmcnt(4)
	v_mfma_f32_32x32x16_bf16 v[50:65], v[158:161], v[162:165], v[50:65]
	v_mfma_f32_32x32x16_bf16 v[34:49], v[158:161], v[166:169], v[34:49]
	v_mfma_f32_32x32x16_bf16 v[18:33], v[214:217], v[162:165], v[18:33]
	v_mfma_f32_32x32x16_bf16 v[2:17], v[214:217], v[166:169], v[2:17]
	ds_read_b128 v[158:161], v140 offset:36928
	ds_read_b128 v[162:165], v141 offset:55360
	ds_read_b128 v[166:169], v141 offset:59968
	ds_read_b128 v[214:217], v140 offset:41536
	s_waitcnt lgkmcnt(4)
	v_mfma_f32_32x32x16_bf16 v[50:65], v[218:221], v[222:225], v[50:65]
	v_mfma_f32_32x32x16_bf16 v[34:49], v[218:221], v[226:229], v[34:49]
	v_mfma_f32_32x32x16_bf16 v[18:33], v[230:233], v[222:225], v[18:33]
	v_mfma_f32_32x32x16_bf16 v[2:17], v[230:233], v[226:229], v[2:17]
	ds_read_b128 v[218:221], v140 offset:36960
	ds_read_b128 v[222:225], v141 offset:55392
	ds_read_b128 v[226:229], v141 offset:60000
	ds_read_b128 v[230:233], v140 offset:41568
	s_waitcnt lgkmcnt(4)
	v_mfma_f32_32x32x16_bf16 v[50:65], v[158:161], v[162:165], v[50:65]
	v_mfma_f32_32x32x16_bf16 v[34:49], v[158:161], v[166:169], v[34:49]
	v_mfma_f32_32x32x16_bf16 v[18:33], v[214:217], v[162:165], v[18:33]
	v_mfma_f32_32x32x16_bf16 v[2:17], v[214:217], v[166:169], v[2:17]
	s_waitcnt lgkmcnt(0)
	v_mfma_f32_32x32x16_bf16 v[50:65], v[218:221], v[222:225], v[50:65]
	v_mfma_f32_32x32x16_bf16 v[34:49], v[218:221], v[226:229], v[34:49]
	v_mfma_f32_32x32x16_bf16 v[18:33], v[230:233], v[222:225], v[18:33]
	v_mfma_f32_32x32x16_bf16 v[2:17], v[230:233], v[226:229], v[2:17]
	s_setprio 0
	s_and_b64 vcc, exec, s[0:1]
	s_waitcnt vmcnt(8)
	ds_write_b128 v188, v[86:89]
	ds_write_b128 v188, v[98:101] offset:4608
	ds_write_b128 v188, v[102:105] offset:9216
	ds_write_b128 v188, v[110:113] offset:13824
	ds_write_b128 v188, v[114:117] offset:18432
	ds_write_b128 v188, v[118:121] offset:23040
	ds_write_b128 v188, v[122:125] offset:27648
	ds_write_b128 v188, v[126:129] offset:32256
	s_waitcnt lgkmcnt(0)
	s_barrier
	s_cbranch_vccnz .LBB0_611
	v_add_co_u32_e32 v98, vcc, 0x10000, v132
	global_load_dwordx4 v[86:89], v[132:133], off
	s_nop 0
	v_addc_co_u32_e32 v99, vcc, 0, v133, vcc
	v_add_co_u32_e32 v102, vcc, 0x20000, v132
	s_nop 1
	v_addc_co_u32_e32 v103, vcc, 0, v133, vcc
	v_add_co_u32_e32 v110, vcc, 0x30000, v132
	global_load_dwordx4 v[98:101], v[98:99], off
	s_nop 0
	global_load_dwordx4 v[102:105], v[102:103], off
	v_addc_co_u32_e32 v111, vcc, 0, v133, vcc
	v_add_co_u32_e32 v118, vcc, 0x10000, v134
	global_load_dwordx4 v[110:113], v[110:111], off
	s_nop 0
	global_load_dwordx4 v[114:117], v[134:135], off
	v_addc_co_u32_e32 v119, vcc, 0, v135, vcc
	v_add_co_u32_e32 v122, vcc, 0x20000, v134
	s_nop 1
	v_addc_co_u32_e32 v123, vcc, 0, v135, vcc
	v_add_co_u32_e32 v126, vcc, 0x30000, v134
	global_load_dwordx4 v[118:121], v[118:119], off
	s_nop 0
	global_load_dwordx4 v[122:125], v[122:123], off
	v_addc_co_u32_e32 v127, vcc, 0, v135, vcc
	global_load_dwordx4 v[126:129], v[126:127], off
